# gain abs-max product hoisted to the attention / memory-attention unit-loop preheaders (kept in s100); weight-transpose jobs prefetch the other 7 rows of an item right after its first row load
# speedup vs baseline: 1.0038x; 1.0038x over previous
.LBB0_610:
	s_mov_b64 s[4:5], s[0:1]
	s_load_dwordx2 s[10:11], s[4:5], 0x68
	s_mov_b64 s[4:5], s[0:1]
	s_load_dwordx2 s[20:21], s[4:5], 0x60
	s_mov_b64 s[4:5], s[0:1]
	s_waitcnt lgkmcnt(0)
	s_add_u32 s13, s10, s6
	s_addc_u32 s25, s11, s7
	s_mul_hi_i32 s10, s14, 0x2e8ba2e9
	s_add_u32 s18, s20, s8
	s_addc_u32 s19, s21, s9
	s_lshr_b32 s11, s10, 31
	s_ashr_i32 s10, s10, 5
	s_add_i32 s10, s10, s11
	s_lshl_b32 s12, s10, 6
	s_mulk_i32 s10, 0xea00
	s_add_i32 s10, s15, s10
	s_ashr_i32 s11, s10, 31
	s_lshl_b64 s[22:23], s[10:11], 2
	s_add_u32 s22, s13, s22
	s_addc_u32 s23, s25, s23
	s_waitcnt vmcnt(0)
	v_lshl_add_u64 v[4:5], s[22:23], 0, v[112:113]
	v_or_b32_e32 v6, s12, v8
	v_mad_i64_i32 v[0:1], s[22:23], v6, s74, v[4:5]
	global_load_dwordx4 v[0:3], v[0:1], off
	v_or_b32_e32 v46, s12, v11
	v_mad_i64_i32 v[48:49], vcc, v46, s74, v[4:5]
	global_load_dwordx4 v[74:77], v[48:49], off
	v_or_b32_e32 v46, s12, v13
	v_mad_i64_i32 v[48:49], vcc, v46, s74, v[4:5]
	global_load_dwordx4 v[78:81], v[48:49], off
	v_or_b32_e32 v46, s12, v16
	v_mad_i64_i32 v[48:49], vcc, v46, s74, v[4:5]
	global_load_dwordx4 v[82:85], v[48:49], off
	v_or_b32_e32 v46, s12, v17
	v_mad_i64_i32 v[48:49], vcc, v46, s74, v[4:5]
	global_load_dwordx4 v[86:89], v[48:49], off
	v_or_b32_e32 v46, s12, v18
	v_mad_i64_i32 v[48:49], vcc, v46, s74, v[4:5]
	global_load_dwordx4 v[90:93], v[48:49], off
	v_or_b32_e32 v46, s12, v19
	v_mad_i64_i32 v[48:49], vcc, v46, s74, v[4:5]
	global_load_dwordx4 v[94:97], v[48:49], off
	v_or_b32_e32 v46, s12, v20
	v_mad_i64_i32 v[48:49], vcc, v46, s74, v[4:5]
	global_load_dwordx4 v[98:101], v[48:49], off
	s_cmp_lg_u64 s[20:21], 0
	s_cselect_b64 s[22:23], -1, 0
	s_cmp_eq_u64 s[20:21], 0
	s_cbranch_scc1 .LBB0_612
	v_ashrrev_i32_e32 v7, 31, v6
	v_lshl_add_u64 v[6:7], v[6:7], 2, s[18:19]
	global_load_dword v6, v[6:7], off
	s_waitcnt vmcnt(0)
	v_pk_mul_f32 v[2:3], v[2:3], v[6:7] op_sel_hi:[1,0]
	v_pk_mul_f32 v[0:1], v[0:1], v[6:7] op_sel_hi:[1,0]

.LBB0_627:
	s_waitcnt vmcnt(0)
	v_add_u32_e32 v0, 0x1ce0, v24
	ds_write2_b32 v0, v4, v5 offset1:1
	v_add_u32_e32 v0, 0x1ce8, v24
	ds_write2_b32 v0, v6, v7 offset1:1
	s_waitcnt lgkmcnt(0)
	ds_read2_b32 v[6:7], v23 offset0:33 offset1:41
	ds_read2_b32 v[26:27], v23 offset1:8
	s_lshl_b64 s[4:5], s[12:13], 1
	s_waitcnt lgkmcnt(0)
	s_add_u32 s4, s20, s4
	s_addc_u32 s5, s21, s5
	v_mov_b32_e32 v15, v113
	v_lshl_add_u64 v[0:1], s[4:5], 0, v[14:15]
	s_mov_b64 s[4:5], 0x4100000
	v_add_u32_e32 v15, s10, v8
	v_lshl_add_u64 v[4:5], v[0:1], 0, s[4:5]
	v_cvt_pk_bf16_f32 v0, v26, v6
	v_cmp_lt_i32_e32 vcc, s85, v15
	v_add_u32_e32 v6, 0xfffff500, v15
	ds_read2_b32 v[28:29], v23 offset0:66 offset1:74
	ds_read2_b32 v[30:31], v23 offset0:99 offset1:107
	v_cndmask_b32_e32 v6, v15, v6, vcc
	ds_read2_b32 v[32:33], v23 offset0:132 offset1:140
	ds_read2_b32 v[34:35], v23 offset0:165 offset1:173
	ds_read2_b32 v[36:37], v23 offset0:198 offset1:206
	ds_read2_b32 v[38:39], v23 offset0:231 offset1:239
	v_lshlrev_b32_e32 v25, 1, v6
	v_and_b32_e32 v25, 0xffffff00, v25
	v_cndmask_b32_e32 v26, 0, v230, vcc
	v_and_b32_e32 v6, 0x67, v6
	v_or3_b32 v40, v6, v26, v25
	v_ashrrev_i32_e32 v41, 31, v40
	v_lshlrev_b64 v[40:41], 11, v[40:41]
	s_waitcnt lgkmcnt(4)
	v_cvt_pk_bf16_f32 v1, v28, v30
	s_waitcnt lgkmcnt(2)
	v_cvt_pk_bf16_f32 v2, v32, v34
	s_waitcnt lgkmcnt(0)
	v_cvt_pk_bf16_f32 v3, v36, v38
	v_lshl_add_u64 v[40:41], v[4:5], 0, v[40:41]
	v_add_u32_e32 v6, 8, v15
	global_store_dwordx4 v[40:41], v[0:3], off
	v_cmp_lt_i32_e32 vcc, s85, v6
	s_add_i32 s10, s28, s14
	v_cvt_pk_bf16_f32 v0, v27, v7
	v_add_u32_e32 v7, 0xfffff508, v15
	v_cndmask_b32_e32 v6, v6, v7, vcc
	v_lshlrev_b32_e32 v7, 1, v6
	v_and_b32_e32 v7, 0xffffff00, v7
	v_cndmask_b32_e32 v25, 0, v230, vcc
	v_and_b32_e32 v6, 0x6f, v6
	v_or3_b32 v6, v6, v25, v7
	v_ashrrev_i32_e32 v7, 31, v6
	v_lshlrev_b64 v[6:7], 11, v[6:7]
	v_cvt_pk_bf16_f32 v1, v29, v31
	v_cvt_pk_bf16_f32 v2, v33, v35
	v_cvt_pk_bf16_f32 v3, v37, v39
	v_lshl_add_u64 v[6:7], v[4:5], 0, v[6:7]
	global_store_dwordx4 v[6:7], v[0:3], off
	ds_read2_b32 v[6:7], v23 offset0:16 offset1:24
	ds_read2_b32 v[26:27], v23 offset0:49 offset1:57
	v_add_u32_e32 v25, 0xfffff510, v15
	ds_read2_b32 v[28:29], v23 offset0:82 offset1:90
	ds_read2_b32 v[30:31], v23 offset0:115 offset1:123
	ds_read2_b32 v[32:33], v23 offset0:148 offset1:156
	ds_read2_b32 v[34:35], v23 offset0:181 offset1:189
	ds_read2_b32 v[36:37], v23 offset0:214 offset1:222
	ds_read2_b32 v[38:39], v23 offset0:247 offset1:255
	s_waitcnt lgkmcnt(6)
	v_cvt_pk_bf16_f32 v0, v6, v26
	v_add_u32_e32 v6, 16, v15
	v_cmp_lt_i32_e32 vcc, s85, v6
	s_waitcnt lgkmcnt(4)
	v_cvt_pk_bf16_f32 v1, v28, v30
	s_waitcnt lgkmcnt(2)
	v_cvt_pk_bf16_f32 v2, v32, v34
	v_cndmask_b32_e32 v6, v6, v25, vcc
	v_lshlrev_b32_e32 v25, 1, v6
	v_and_b32_e32 v25, 0xffffff00, v25
	v_cndmask_b32_e32 v26, 0, v230, vcc
	v_and_b32_e32 v6, 0x77, v6
	v_or3_b32 v40, v6, v26, v25
	v_ashrrev_i32_e32 v41, 31, v40
	v_lshlrev_b64 v[40:41], 11, v[40:41]
	s_waitcnt lgkmcnt(0)
	v_cvt_pk_bf16_f32 v3, v36, v38
	v_lshl_add_u64 v[40:41], v[4:5], 0, v[40:41]
	global_store_dwordx4 v[40:41], v[0:3], off
	s_cmpk_gt_i32 s10, 0xaff
	s_nop 0
	v_add_u32_e32 v0, 24, v15
	v_cmp_lt_i32_e32 vcc, s85, v0
	v_add_u32_e32 v1, 0xfffff518, v15
	v_cvt_pk_bf16_f32 v3, v37, v39
	v_cndmask_b32_e32 v0, v0, v1, vcc
	v_lshlrev_b32_e32 v1, 1, v0
	v_and_b32_e32 v1, 0xffffff00, v1
	v_cndmask_b32_e32 v2, 0, v230, vcc
	v_and_b32_e32 v0, 0x7f, v0
	v_or3_b32 v6, v0, v2, v1
	v_cvt_pk_bf16_f32 v0, v7, v27
	v_ashrrev_i32_e32 v7, 31, v6
	v_lshlrev_b64 v[6:7], 11, v[6:7]
	v_cvt_pk_bf16_f32 v1, v29, v31
	v_cvt_pk_bf16_f32 v2, v33, v35
	v_lshl_add_u64 v[4:5], v[4:5], 0, v[6:7]
	global_store_dwordx4 v[4:5], v[0:3], off
	s_waitcnt lgkmcnt(0)
	s_cbranch_scc1 .LBB0_609
	s_mov_b64 s[4:5], s[0:1]
	s_load_dwordx2 s[12:13], s[4:5], 0x68
	s_mov_b64 s[4:5], s[0:1]
	s_load_dwordx2 s[20:21], s[4:5], 0x60
	s_mul_hi_i32 s11, s10, 0x2e8ba2e9
	s_waitcnt lgkmcnt(0)
	s_add_u32 s25, s12, s6
	s_addc_u32 s13, s13, s7
	s_mov_b64 s[4:5], s[0:1]
	s_add_u32 s18, s20, s8
	s_addc_u32 s19, s21, s9
	s_lshr_b32 s12, s11, 31
	s_ashr_i32 s11, s11, 5
	s_add_i32 s11, s11, s12
	s_mul_i32 s12, s11, 0xb0
	s_sub_i32 s10, s10, s12
	s_lshl_b32 s10, s10, 5
	s_lshl_b32 s12, s11, 6
	s_ashr_i32 s11, s10, 31
	s_lshl_b64 s[22:23], s[10:11], 2
	s_add_u32 s22, s25, s22
	s_addc_u32 s23, s13, s23
	v_lshl_add_u64 v[4:5], s[22:23], 0, v[112:113]
	v_or_b32_e32 v6, s12, v8
	v_mad_i64_i32 v[0:1], s[22:23], v6, s74, v[4:5]
	global_load_dwordx4 v[0:3], v[0:1], off
	v_or_b32_e32 v46, s12, v11
	v_mad_i64_i32 v[48:49], vcc, v46, s74, v[4:5]
	global_load_dwordx4 v[74:77], v[48:49], off
	v_or_b32_e32 v46, s12, v13
	v_mad_i64_i32 v[48:49], vcc, v46, s74, v[4:5]
	global_load_dwordx4 v[78:81], v[48:49], off
	v_or_b32_e32 v46, s12, v16
	v_mad_i64_i32 v[48:49], vcc, v46, s74, v[4:5]
	global_load_dwordx4 v[82:85], v[48:49], off
	v_or_b32_e32 v46, s12, v17
	v_mad_i64_i32 v[48:49], vcc, v46, s74, v[4:5]
	global_load_dwordx4 v[86:89], v[48:49], off
	v_or_b32_e32 v46, s12, v18
	v_mad_i64_i32 v[48:49], vcc, v46, s74, v[4:5]
	global_load_dwordx4 v[90:93], v[48:49], off
	v_or_b32_e32 v46, s12, v19
	v_mad_i64_i32 v[48:49], vcc, v46, s74, v[4:5]
	global_load_dwordx4 v[94:97], v[48:49], off
	v_or_b32_e32 v46, s12, v20
	v_mad_i64_i32 v[48:49], vcc, v46, s74, v[4:5]
	global_load_dwordx4 v[98:101], v[48:49], off
	s_cmp_lg_u64 s[20:21], 0
	s_cselect_b64 s[22:23], -1, 0
	s_cmp_eq_u64 s[20:21], 0
	s_cbranch_scc1 .LBB0_630
	v_ashrrev_i32_e32 v7, 31, v6
	v_lshl_add_u64 v[6:7], v[6:7], 2, s[18:19]
	global_load_dword v6, v[6:7], off
	s_waitcnt vmcnt(0)
	v_pk_mul_f32 v[2:3], v[2:3], v[6:7] op_sel_hi:[1,0]
	v_pk_mul_f32 v[0:1], v[0:1], v[6:7] op_sel_hi:[1,0]

.LBB0_650:
	s_mov_b64 s[8:9], s[0:1]
	s_load_dwordx2 s[8:9], s[8:9], 0x70
	v_lshlrev_b32_e32 v112, 2, v10
	s_waitcnt vmcnt(0)
	v_add_u32_e32 v5, 0x420, v4
	s_waitcnt lgkmcnt(0)
	s_add_u32 s11, s8, s6
	s_addc_u32 s18, s9, s7
	s_ashr_i32 s5, s14, 31
	s_lshr_b32 s5, s5, 27
	s_add_i32 s5, s14, s5
	s_ashr_i32 s5, s5, 5
	s_lshl_b32 s12, s5, 10
	s_sub_i32 s12, s15, s12
	s_ashr_i32 s13, s12, 31
	s_lshl_b32 s10, s5, 6
	s_lshl_b64 s[12:13], s[12:13], 2
	s_add_u32 s12, s11, s12
	v_or_b32_e32 v6, s10, v8
	s_addc_u32 s13, s18, s13
	v_ashrrev_i32_e32 v7, 31, v6
	v_lshl_add_u64 v[0:1], s[12:13], 0, v[112:113]
	v_lshlrev_b64 v[6:7], 12, v[6:7]
	s_mov_b64 s[8:9], s[0:1]
	v_lshl_add_u64 v[6:7], v[0:1], 0, v[6:7]
	global_load_dwordx4 v[24:27], v[6:7], off
	v_or_b32_e32 v46, s10, v11
	v_ashrrev_i32_e32 v47, 31, v46
	v_lshlrev_b64 v[48:49], 12, v[46:47]
	v_lshl_add_u64 v[50:51], v[0:1], 0, v[48:49]
	global_load_dwordx4 v[74:77], v[50:51], off
	v_or_b32_e32 v46, s10, v13
	v_ashrrev_i32_e32 v47, 31, v46
	v_lshlrev_b64 v[48:49], 12, v[46:47]
	v_lshl_add_u64 v[50:51], v[0:1], 0, v[48:49]
	global_load_dwordx4 v[78:81], v[50:51], off
	v_or_b32_e32 v46, s10, v16
	v_ashrrev_i32_e32 v47, 31, v46
	v_lshlrev_b64 v[48:49], 12, v[46:47]
	v_lshl_add_u64 v[50:51], v[0:1], 0, v[48:49]
	global_load_dwordx4 v[82:85], v[50:51], off
	v_or_b32_e32 v46, s10, v17
	v_ashrrev_i32_e32 v47, 31, v46
	v_lshlrev_b64 v[48:49], 12, v[46:47]
	v_lshl_add_u64 v[50:51], v[0:1], 0, v[48:49]
	global_load_dwordx4 v[86:89], v[50:51], off
	v_or_b32_e32 v46, s10, v18
	v_ashrrev_i32_e32 v47, 31, v46
	v_lshlrev_b64 v[48:49], 12, v[46:47]
	v_lshl_add_u64 v[50:51], v[0:1], 0, v[48:49]
	global_load_dwordx4 v[90:93], v[50:51], off
	v_or_b32_e32 v46, s10, v19
	v_ashrrev_i32_e32 v47, 31, v46
	v_lshlrev_b64 v[48:49], 12, v[46:47]
	v_lshl_add_u64 v[50:51], v[0:1], 0, v[48:49]
	global_load_dwordx4 v[94:97], v[50:51], off
	v_or_b32_e32 v46, s10, v20
	v_ashrrev_i32_e32 v47, 31, v46
	v_lshlrev_b64 v[48:49], 12, v[46:47]
	v_lshl_add_u64 v[50:51], v[0:1], 0, v[48:49]
	global_load_dwordx4 v[98:101], v[50:51], off
	v_or_b32_e32 v6, s10, v11
	v_ashrrev_i32_e32 v7, 31, v6
	v_lshlrev_b64 v[6:7], 12, v[6:7]
	s_load_dwordx2 s[8:9], s[8:9], 0xe8
	v_lshl_add_u64 v[6:7], v[0:1], 0, v[6:7]
	s_ashr_i32 s11, s10, 31
	s_mul_i32 s5, s5, 0xffd40000
	v_add_u32_e32 v42, s5, v3
	v_ashrrev_i32_e32 v43, 31, v42
	s_waitcnt vmcnt(0)
	ds_write2_b32 v4, v24, v25 offset1:1
	ds_write2_b32 v4, v26, v27 offset0:2 offset1:3
	global_load_dwordx4 v[24:27], v[6:7], off
	v_or_b32_e32 v6, s10, v13
	v_ashrrev_i32_e32 v7, 31, v6
	v_lshlrev_b64 v[6:7], 12, v[6:7]
	v_lshl_add_u64 v[6:7], v[0:1], 0, v[6:7]
	s_waitcnt vmcnt(0)
	ds_write2_b32 v5, v24, v25 offset1:1
	v_add_u32_e32 v5, 0x428, v4
	ds_write2_b32 v5, v26, v27 offset1:1
	global_load_dwordx4 v[24:27], v[6:7], off
	v_or_b32_e32 v6, s10, v16
	v_ashrrev_i32_e32 v7, 31, v6
	v_add_u32_e32 v5, 0x840, v4
	v_lshlrev_b64 v[6:7], 12, v[6:7]
	v_lshl_add_u64 v[6:7], v[0:1], 0, v[6:7]
	s_waitcnt vmcnt(0)
	ds_write2_b32 v5, v24, v25 offset1:1
	v_add_u32_e32 v5, 0x848, v4
	ds_write2_b32 v5, v26, v27 offset1:1
	global_load_dwordx4 v[24:27], v[6:7], off
	v_or_b32_e32 v6, s10, v17
	v_ashrrev_i32_e32 v7, 31, v6
	v_add_u32_e32 v5, 0xc60, v4
	v_lshlrev_b64 v[6:7], 12, v[6:7]
	v_lshl_add_u64 v[6:7], v[0:1], 0, v[6:7]
	s_waitcnt vmcnt(0)
	ds_write2_b32 v5, v24, v25 offset1:1
	v_add_u32_e32 v5, 0xc68, v4
	ds_write2_b32 v5, v26, v27 offset1:1
	global_load_dwordx4 v[24:27], v[6:7], off
	v_or_b32_e32 v6, s10, v18
	v_ashrrev_i32_e32 v7, 31, v6
	v_add_u32_e32 v5, 0x1080, v4
	v_lshlrev_b64 v[6:7], 12, v[6:7]
	v_lshl_add_u64 v[6:7], v[0:1], 0, v[6:7]
	s_waitcnt vmcnt(0)
	ds_write2_b32 v5, v24, v25 offset1:1
	v_add_u32_e32 v5, 0x1088, v4
	ds_write2_b32 v5, v26, v27 offset1:1
	global_load_dwordx4 v[24:27], v[6:7], off
	v_or_b32_e32 v6, s10, v19
	v_ashrrev_i32_e32 v7, 31, v6
	v_add_u32_e32 v5, 0x14a0, v4
	v_lshlrev_b64 v[6:7], 12, v[6:7]
	v_lshl_add_u64 v[6:7], v[0:1], 0, v[6:7]
	s_waitcnt vmcnt(0)
	ds_write2_b32 v5, v24, v25 offset1:1
	v_add_u32_e32 v5, 0x14a8, v4
	ds_write2_b32 v5, v26, v27 offset1:1
	global_load_dwordx4 v[24:27], v[6:7], off
	v_or_b32_e32 v6, s10, v20
	v_ashrrev_i32_e32 v7, 31, v6
	v_add_u32_e32 v5, 0x18c0, v4
	v_lshlrev_b64 v[6:7], 12, v[6:7]
	v_lshl_add_u64 v[0:1], v[0:1], 0, v[6:7]
	s_lshl_b64 s[10:11], s[10:11], 1
	s_waitcnt lgkmcnt(0)
	s_add_u32 s8, s8, s10
	s_addc_u32 s9, s9, s11
	s_add_i32 s5, s28, s14
	s_cmpk_gt_i32 s5, 0x57f
	s_waitcnt vmcnt(0)
	ds_write2_b32 v5, v24, v25 offset1:1
	v_add_u32_e32 v5, 0x18c8, v4
	ds_write2_b32 v5, v26, v27 offset1:1
	global_load_dwordx4 v[24:27], v[0:1], off
	v_add_u32_e32 v0, 0x1ce0, v4
	v_mov_b32_e32 v1, v113
	s_waitcnt vmcnt(0)
	ds_write2_b32 v0, v24, v25 offset1:1
	v_add_u32_e32 v0, 0x1ce8, v4
	ds_write2_b32 v0, v26, v27 offset1:1
	s_waitcnt lgkmcnt(0)
	ds_read2_b32 v[14:15], v2 offset0:33 offset1:41
	ds_read2_b32 v[28:29], v2 offset1:8
	ds_read2_b32 v[30:31], v2 offset0:66 offset1:74
	ds_read2_b32 v[32:33], v2 offset0:99 offset1:107
	ds_read2_b32 v[34:35], v2 offset0:132 offset1:140
	ds_read2_b32 v[36:37], v2 offset0:165 offset1:173
	ds_read2_b32 v[38:39], v2 offset0:198 offset1:206
	ds_read2_b32 v[40:41], v2 offset0:231 offset1:239
	v_lshlrev_b32_e32 v0, 1, v12
	v_lshl_add_u64 v[6:7], s[8:9], 0, v[0:1]
	s_mov_b64 s[8:9], 0x4c00000
	v_lshl_add_u64 v[6:7], v[6:7], 0, s[8:9]
	s_waitcnt lgkmcnt(6)
	v_cvt_pk_bf16_f32 v24, v28, v14
	s_waitcnt lgkmcnt(4)
	v_cvt_pk_bf16_f32 v25, v30, v32
	s_waitcnt lgkmcnt(2)
	v_cvt_pk_bf16_f32 v26, v34, v36
	s_waitcnt lgkmcnt(0)
	v_cvt_pk_bf16_f32 v27, v38, v40
	v_lshl_add_u64 v[44:45], v[42:43], 1, v[6:7]
	v_add_u32_e32 v14, 0x5800, v42
	global_store_dwordx4 v[44:45], v[24:27], off
	v_add_u32_e32 v44, 0xb000, v42
	v_ashrrev_i32_e32 v45, 31, v44
	v_cvt_pk_bf16_f32 v24, v29, v15
	v_ashrrev_i32_e32 v15, 31, v14
	v_cvt_pk_bf16_f32 v25, v31, v33
	v_cvt_pk_bf16_f32 v26, v35, v37
	v_cvt_pk_bf16_f32 v27, v39, v41
	v_lshl_add_u64 v[14:15], v[14:15], 1, v[6:7]
	global_store_dwordx4 v[14:15], v[24:27], off
	ds_read2_b32 v[14:15], v2 offset0:49 offset1:57
	ds_read2_b32 v[28:29], v2 offset0:16 offset1:24
	ds_read2_b32 v[30:31], v2 offset0:82 offset1:90
	ds_read2_b32 v[32:33], v2 offset0:115 offset1:123
	ds_read2_b32 v[34:35], v2 offset0:148 offset1:156
	ds_read2_b32 v[36:37], v2 offset0:181 offset1:189
	ds_read2_b32 v[38:39], v2 offset0:214 offset1:222
	ds_read2_b32 v[40:41], v2 offset0:247 offset1:255
	v_lshl_add_u64 v[44:45], v[44:45], 1, v[6:7]
	s_waitcnt lgkmcnt(6)
	v_cvt_pk_bf16_f32 v24, v28, v14
	s_waitcnt lgkmcnt(4)
	v_cvt_pk_bf16_f32 v25, v30, v32
	s_waitcnt lgkmcnt(2)
	v_cvt_pk_bf16_f32 v26, v34, v36
	s_waitcnt lgkmcnt(0)
	v_cvt_pk_bf16_f32 v27, v38, v40
	v_add_u32_e32 v14, 0x10800, v42
	global_store_dwordx4 v[44:45], v[24:27], off
	s_nop 1
	v_cvt_pk_bf16_f32 v24, v29, v15
	v_ashrrev_i32_e32 v15, 31, v14
	v_cvt_pk_bf16_f32 v25, v31, v33
	v_cvt_pk_bf16_f32 v26, v35, v37
	v_cvt_pk_bf16_f32 v27, v39, v41
	v_lshl_add_u64 v[6:7], v[14:15], 1, v[6:7]
	global_store_dwordx4 v[6:7], v[24:27], off
	s_waitcnt lgkmcnt(0)
	s_cbranch_scc1 .LBB0_649
	s_mov_b64 s[8:9], s[0:1]
	s_load_dwordx2 s[8:9], s[8:9], 0x70
	v_add_u32_e32 v5, 0x2100, v4
	v_add_u32_e32 v9, 0x2400, v2
	s_movk_i32 s3, 0xb00
	s_waitcnt lgkmcnt(0)
	s_add_u32 s13, s8, s6
	s_addc_u32 s20, s9, s7
	s_mov_b64 s[8:9], s[0:1]
	s_load_dwordx2 s[10:11], s[8:9], 0xe8
	s_ashr_i32 s8, s5, 31
	s_lshr_b32 s8, s8, 27
	s_add_i32 s8, s5, s8
	s_and_b32 s9, s8, 0x7ffffe0
	s_sub_i32 s5, s5, s9
	s_lshl_b32 s8, s8, 1
	s_and_b32 s12, s8, 0xffffffc0
	s_lshl_b32 s8, s5, 5
	s_ashr_i32 s9, s8, 31
	s_lshl_b64 s[18:19], s[8:9], 2
	s_add_u32 s18, s13, s18
	v_or_b32_e32 v14, s12, v8
	s_addc_u32 s19, s20, s19
	v_ashrrev_i32_e32 v15, 31, v14
	v_lshl_add_u64 v[6:7], s[18:19], 0, v[112:113]
	v_lshlrev_b64 v[14:15], 12, v[14:15]
	v_lshl_add_u64 v[14:15], v[6:7], 0, v[14:15]
	global_load_dwordx4 v[24:27], v[14:15], off
	v_or_b32_e32 v46, s12, v11
	v_ashrrev_i32_e32 v47, 31, v46
	v_lshlrev_b64 v[48:49], 12, v[46:47]
	v_lshl_add_u64 v[50:51], v[6:7], 0, v[48:49]
	global_load_dwordx4 v[74:77], v[50:51], off
	v_or_b32_e32 v46, s12, v13
	v_ashrrev_i32_e32 v47, 31, v46
	v_lshlrev_b64 v[48:49], 12, v[46:47]
	v_lshl_add_u64 v[50:51], v[6:7], 0, v[48:49]
	global_load_dwordx4 v[78:81], v[50:51], off
	v_or_b32_e32 v46, s12, v16
	v_ashrrev_i32_e32 v47, 31, v46
	v_lshlrev_b64 v[48:49], 12, v[46:47]
	v_lshl_add_u64 v[50:51], v[6:7], 0, v[48:49]
	global_load_dwordx4 v[82:85], v[50:51], off
	v_or_b32_e32 v46, s12, v17
	v_ashrrev_i32_e32 v47, 31, v46
	v_lshlrev_b64 v[48:49], 12, v[46:47]
	v_lshl_add_u64 v[50:51], v[6:7], 0, v[48:49]
	global_load_dwordx4 v[86:89], v[50:51], off
	v_or_b32_e32 v46, s12, v18
	v_ashrrev_i32_e32 v47, 31, v46
	v_lshlrev_b64 v[48:49], 12, v[46:47]
	v_lshl_add_u64 v[50:51], v[6:7], 0, v[48:49]
	global_load_dwordx4 v[90:93], v[50:51], off
	v_or_b32_e32 v46, s12, v19
	v_ashrrev_i32_e32 v47, 31, v46
	v_lshlrev_b64 v[48:49], 12, v[46:47]
	v_lshl_add_u64 v[50:51], v[6:7], 0, v[48:49]
	global_load_dwordx4 v[94:97], v[50:51], off
	v_or_b32_e32 v46, s12, v20
	v_ashrrev_i32_e32 v47, 31, v46
	v_lshlrev_b64 v[48:49], 12, v[46:47]
	v_lshl_add_u64 v[50:51], v[6:7], 0, v[48:49]
	global_load_dwordx4 v[98:101], v[50:51], off
	v_or_b32_e32 v14, s12, v11
	v_ashrrev_i32_e32 v15, 31, v14
	v_lshlrev_b64 v[14:15], 12, v[14:15]
	v_lshl_add_u64 v[14:15], v[6:7], 0, v[14:15]
	s_ashr_i32 s13, s12, 31
	s_waitcnt vmcnt(0)
	ds_write2_b32 v5, v24, v25 offset1:1
	v_add_u32_e32 v5, 0x2108, v4
	ds_write2_b32 v5, v26, v27 offset1:1
	global_load_dwordx4 v[24:27], v[14:15], off
	v_or_b32_e32 v14, s12, v13
	v_ashrrev_i32_e32 v15, 31, v14
	v_add_u32_e32 v5, 0x2520, v4
	v_lshlrev_b64 v[14:15], 12, v[14:15]
	v_lshl_add_u64 v[14:15], v[6:7], 0, v[14:15]
	s_waitcnt vmcnt(0)
	ds_write2_b32 v5, v24, v25 offset1:1
	v_add_u32_e32 v5, 0x2528, v4
	ds_write2_b32 v5, v26, v27 offset1:1
	global_load_dwordx4 v[24:27], v[14:15], off
	v_or_b32_e32 v14, s12, v16
	v_ashrrev_i32_e32 v15, 31, v14
	v_add_u32_e32 v5, 0x2940, v4
	v_lshlrev_b64 v[14:15], 12, v[14:15]
	v_lshl_add_u64 v[14:15], v[6:7], 0, v[14:15]
	s_waitcnt vmcnt(0)
	ds_write2_b32 v5, v24, v25 offset1:1
	v_add_u32_e32 v5, 0x2948, v4
	ds_write2_b32 v5, v26, v27 offset1:1
	global_load_dwordx4 v[24:27], v[14:15], off
	v_or_b32_e32 v14, s12, v17
	v_ashrrev_i32_e32 v15, 31, v14
	v_add_u32_e32 v5, 0x2d60, v4
	v_lshlrev_b64 v[14:15], 12, v[14:15]
	v_lshl_add_u64 v[14:15], v[6:7], 0, v[14:15]
	s_waitcnt vmcnt(0)
	ds_write2_b32 v5, v24, v25 offset1:1
	v_add_u32_e32 v5, 0x2d68, v4
	ds_write2_b32 v5, v26, v27 offset1:1
	global_load_dwordx4 v[24:27], v[14:15], off
	v_or_b32_e32 v14, s12, v18
	v_ashrrev_i32_e32 v15, 31, v14
	v_add_u32_e32 v5, 0x3180, v4
	v_lshlrev_b64 v[14:15], 12, v[14:15]
	v_lshl_add_u64 v[14:15], v[6:7], 0, v[14:15]
	s_waitcnt vmcnt(0)
	ds_write2_b32 v5, v24, v25 offset1:1
	v_add_u32_e32 v5, 0x3188, v4
	ds_write2_b32 v5, v26, v27 offset1:1
	global_load_dwordx4 v[24:27], v[14:15], off
	v_or_b32_e32 v14, s12, v19
	v_ashrrev_i32_e32 v15, 31, v14
	v_add_u32_e32 v5, 0x35a0, v4
	v_lshlrev_b64 v[14:15], 12, v[14:15]
	v_lshl_add_u64 v[14:15], v[6:7], 0, v[14:15]
	s_waitcnt vmcnt(0)
	ds_write2_b32 v5, v24, v25 offset1:1
	v_add_u32_e32 v5, 0x35a8, v4
	ds_write2_b32 v5, v26, v27 offset1:1
	global_load_dwordx4 v[24:27], v[14:15], off
	v_or_b32_e32 v14, s12, v20
	v_ashrrev_i32_e32 v15, 31, v14
	v_add_u32_e32 v5, 0x39c0, v4
	v_lshlrev_b64 v[14:15], 12, v[14:15]
	v_lshl_add_u64 v[6:7], v[6:7], 0, v[14:15]
	s_lshl_b64 s[12:13], s[12:13], 1
	s_waitcnt lgkmcnt(0)
	s_add_u32 s10, s10, s12
	s_addc_u32 s11, s11, s13
	v_lshl_add_u64 v[0:1], s[10:11], 0, v[0:1]
	s_mov_b64 s[10:11], 0x4c00000
	v_lshl_add_u64 v[0:1], v[0:1], 0, s[10:11]
	s_waitcnt vmcnt(0)
	ds_write2_b32 v5, v24, v25 offset1:1
	v_add_u32_e32 v5, 0x39c8, v4
	ds_write2_b32 v5, v26, v27 offset1:1
	global_load_dwordx4 v[24:27], v[6:7], off
	v_add_u32_e32 v5, 0x3de0, v4
	s_waitcnt vmcnt(0)
	ds_write2_b32 v5, v24, v25 offset1:1
	v_add_u32_e32 v5, 0x3de8, v4
	ds_write2_b32 v5, v26, v27 offset1:1
	s_waitcnt lgkmcnt(0)
	v_add_u32_e32 v5, 0x2000, v2
	ds_read2_b32 v[6:7], v5 offset0:97 offset1:105
	ds_read2_b32 v[14:15], v5 offset0:64 offset1:72
	ds_read2_b32 v[28:29], v5 offset0:130 offset1:138
	ds_read2_b32 v[30:31], v5 offset0:163 offset1:171
	ds_read2_b32 v[32:33], v5 offset0:196 offset1:204
	ds_read2_b32 v[34:35], v5 offset0:229 offset1:237
	ds_read2_b32 v[36:37], v9 offset0:6 offset1:14
	ds_read2_b32 v[38:39], v9 offset0:39 offset1:47
	s_waitcnt lgkmcnt(6)
	v_cvt_pk_bf16_f32 v24, v14, v6
	v_or_b32_e32 v6, s8, v8
	v_mul_lo_u32 v40, v6, s3
	v_ashrrev_i32_e32 v41, 31, v40
	v_or_b32_e32 v6, s8, v11
	s_waitcnt lgkmcnt(4)
	v_cvt_pk_bf16_f32 v25, v28, v30
	s_waitcnt lgkmcnt(2)
	v_cvt_pk_bf16_f32 v26, v32, v34
	s_waitcnt lgkmcnt(0)
	v_cvt_pk_bf16_f32 v27, v36, v38
	v_lshl_add_u64 v[40:41], v[40:41], 1, v[0:1]
	v_mul_lo_u32 v6, v6, s3
	global_store_dwordx4 v[40:41], v[24:27], off
	s_nop 1
	v_cvt_pk_bf16_f32 v24, v15, v7
	v_ashrrev_i32_e32 v7, 31, v6
	v_cvt_pk_bf16_f32 v25, v29, v31
	v_cvt_pk_bf16_f32 v26, v33, v35
	v_cvt_pk_bf16_f32 v27, v37, v39
	v_lshl_add_u64 v[6:7], v[6:7], 1, v[0:1]
	global_store_dwordx4 v[6:7], v[24:27], off
	ds_read2_b32 v[6:7], v5 offset0:113 offset1:121
	ds_read2_b32 v[14:15], v5 offset0:80 offset1:88
	ds_read2_b32 v[28:29], v5 offset0:146 offset1:154
	ds_read2_b32 v[30:31], v5 offset0:179 offset1:187
	ds_read2_b32 v[32:33], v5 offset0:212 offset1:220
	ds_read2_b32 v[34:35], v5 offset0:245 offset1:253
	ds_read2_b32 v[36:37], v9 offset0:22 offset1:30
	ds_read2_b32 v[38:39], v9 offset0:55 offset1:63
	v_or_b32_e32 v5, s8, v13
	v_mul_lo_u32 v40, v5, s3
	v_ashrrev_i32_e32 v41, 31, v40
	v_or_b32_e32 v5, s8, v16
	s_waitcnt lgkmcnt(6)
	v_cvt_pk_bf16_f32 v24, v14, v6
	s_waitcnt lgkmcnt(4)
	v_cvt_pk_bf16_f32 v25, v28, v30
	s_waitcnt lgkmcnt(2)
	v_cvt_pk_bf16_f32 v26, v32, v34
	s_waitcnt lgkmcnt(0)
	v_cvt_pk_bf16_f32 v27, v36, v38
	v_lshl_add_u64 v[40:41], v[40:41], 1, v[0:1]
	v_mul_lo_u32 v6, v5, s3
	global_store_dwordx4 v[40:41], v[24:27], off
	s_nop 1
	v_cvt_pk_bf16_f32 v24, v15, v7
	v_ashrrev_i32_e32 v7, 31, v6
	v_cvt_pk_bf16_f32 v25, v29, v31
	v_cvt_pk_bf16_f32 v26, v33, v35
	v_cvt_pk_bf16_f32 v27, v37, v39
	v_lshl_add_u64 v[0:1], v[6:7], 1, v[0:1]
	global_store_dwordx4 v[0:1], v[24:27], off
	s_waitcnt lgkmcnt(0)
	s_branch .LBB0_649

.LBB0_656:
	s_mov_b64 s[10:11], s[0:1]
	s_load_dwordx2 s[10:11], s[10:11], 0x20
	s_waitcnt lgkmcnt(0)
	s_add_u32 s15, s10, s6
	s_addc_u32 s19, s11, s7
	s_mov_b64 s[10:11], s[0:1]
	s_load_dwordx2 s[10:11], s[10:11], 0x18
	s_waitcnt lgkmcnt(0)
	s_add_u32 s20, s10, s8
	s_addc_u32 s21, s11, s9
	s_mov_b64 s[10:11], s[0:1]
	s_load_dwordx2 s[12:13], s[10:11], 0xe8
	s_mul_hi_i32 s10, s5, 0x2e8ba2e9
	s_lshr_b32 s11, s10, 31
	s_ashr_i32 s10, s10, 5
	s_add_i32 s10, s10, s11
	s_lshl_b32 s18, s10, 6
	s_mulk_i32 s10, 0xea00
	s_add_i32 s10, s14, s10
	s_ashr_i32 s11, s10, 31
	s_lshl_b64 s[22:23], s[10:11], 2
	s_add_u32 s22, s15, s22
	s_addc_u32 s23, s19, s23
	v_lshl_add_u64 v[2:3], s[22:23], 0, v[112:113]
	v_or_b32_e32 v6, s18, v8
	v_ashrrev_i32_e32 v7, 31, v6
	v_mad_i64_i32 v[14:15], s[22:23], v6, s74, v[2:3]
	global_load_dwordx4 v[24:27], v[14:15], off
	v_or_b32_e32 v47, s18, v11
	v_mad_i64_i32 v[48:49], vcc, v47, s74, v[2:3]
	global_load_dwordx4 v[74:77], v[48:49], off
	v_or_b32_e32 v47, s18, v13
	v_mad_i64_i32 v[48:49], vcc, v47, s74, v[2:3]
	global_load_dwordx4 v[78:81], v[48:49], off
	v_or_b32_e32 v47, s18, v16
	v_mad_i64_i32 v[48:49], vcc, v47, s74, v[2:3]
	global_load_dwordx4 v[82:85], v[48:49], off
	v_or_b32_e32 v47, s18, v17
	v_mad_i64_i32 v[48:49], vcc, v47, s74, v[2:3]
	global_load_dwordx4 v[86:89], v[48:49], off
	v_or_b32_e32 v47, s18, v18
	v_mad_i64_i32 v[48:49], vcc, v47, s74, v[2:3]
	global_load_dwordx4 v[90:93], v[48:49], off
	v_or_b32_e32 v47, s18, v19
	v_mad_i64_i32 v[48:49], vcc, v47, s74, v[2:3]
	global_load_dwordx4 v[94:97], v[48:49], off
	v_or_b32_e32 v47, s18, v20
	v_mad_i64_i32 v[48:49], vcc, v47, s74, v[2:3]
	global_load_dwordx4 v[98:101], v[48:49], off
	v_lshl_add_u64 v[14:15], v[6:7], 2, s[20:21]
	global_load_dword v14, v[14:15], off
	s_ashr_i32 s19, s18, 31
	v_or_b32_e32 v1, s18, v11
	v_mov_b32_e32 v7, s19
	v_lshl_add_u64 v[6:7], v[6:7], 2, s[20:21]
	v_add_u32_e32 v9, s10, v8
	v_cmp_lt_i32_e32 vcc, s85, v9
	s_waitcnt vmcnt(0)
	v_pk_mul_f32 v[26:27], v[26:27], v[14:15] op_sel_hi:[1,0]
	v_pk_mul_f32 v[14:15], v[24:25], v[14:15] op_sel_hi:[1,0]
	ds_write2_b32 v5, v14, v15 offset1:1
	ds_write2_b32 v5, v26, v27 offset0:2 offset1:3
	v_mad_i64_i32 v[14:15], s[22:23], v1, s74, v[2:3]
	global_load_dwordx4 v[24:27], v[14:15], off
	v_add_u32_e32 v1, 0x420, v5
	global_load_dword v14, v[6:7], off offset:32
	v_cndmask_b32_e32 v23, 0, v230, vcc
	s_waitcnt vmcnt(0)
	v_pk_mul_f32 v[26:27], v[26:27], v[14:15] op_sel_hi:[1,0]
	v_pk_mul_f32 v[14:15], v[24:25], v[14:15] op_sel_hi:[1,0]
	ds_write2_b32 v1, v14, v15 offset1:1
	v_add_u32_e32 v1, 0x428, v5
	ds_write2_b32 v1, v26, v27 offset1:1
	v_or_b32_e32 v1, s18, v13
	v_mad_i64_i32 v[14:15], s[20:21], v1, s74, v[2:3]
	global_load_dwordx4 v[24:27], v[14:15], off
	s_nop 0
	global_load_dword v14, v[6:7], off offset:64
	v_add_u32_e32 v1, 0x840, v5
	s_waitcnt vmcnt(0)
	v_pk_mul_f32 v[26:27], v[26:27], v[14:15] op_sel_hi:[1,0]
	v_pk_mul_f32 v[14:15], v[24:25], v[14:15] op_sel_hi:[1,0]
	ds_write2_b32 v1, v14, v15 offset1:1
	v_add_u32_e32 v1, 0x848, v5
	ds_write2_b32 v1, v26, v27 offset1:1
	v_or_b32_e32 v1, s18, v16
	v_mad_i64_i32 v[14:15], s[20:21], v1, s74, v[2:3]
	global_load_dwordx4 v[24:27], v[14:15], off
	s_nop 0
	global_load_dword v14, v[6:7], off offset:96
	v_add_u32_e32 v1, 0xc60, v5
	s_waitcnt vmcnt(0)
	v_pk_mul_f32 v[26:27], v[26:27], v[14:15] op_sel_hi:[1,0]
	v_pk_mul_f32 v[14:15], v[24:25], v[14:15] op_sel_hi:[1,0]
	ds_write2_b32 v1, v14, v15 offset1:1
	v_add_u32_e32 v1, 0xc68, v5
	ds_write2_b32 v1, v26, v27 offset1:1
	v_or_b32_e32 v1, s18, v17
	v_mad_i64_i32 v[14:15], s[20:21], v1, s74, v[2:3]
	global_load_dwordx4 v[24:27], v[14:15], off
	s_nop 0
	global_load_dword v14, v[6:7], off offset:128
	v_add_u32_e32 v1, 0x1080, v5
	s_waitcnt vmcnt(0)
	v_pk_mul_f32 v[26:27], v[26:27], v[14:15] op_sel_hi:[1,0]
	v_pk_mul_f32 v[14:15], v[24:25], v[14:15] op_sel_hi:[1,0]
	ds_write2_b32 v1, v14, v15 offset1:1
	v_add_u32_e32 v1, 0x1088, v5
	ds_write2_b32 v1, v26, v27 offset1:1
	v_or_b32_e32 v1, s18, v18
	v_mad_i64_i32 v[14:15], s[20:21], v1, s74, v[2:3]
	global_load_dwordx4 v[24:27], v[14:15], off
	s_nop 0
	global_load_dword v14, v[6:7], off offset:160
	v_add_u32_e32 v1, 0x14a0, v5
	s_waitcnt vmcnt(0)
	v_pk_mul_f32 v[26:27], v[26:27], v[14:15] op_sel_hi:[1,0]
	v_pk_mul_f32 v[14:15], v[24:25], v[14:15] op_sel_hi:[1,0]
	ds_write2_b32 v1, v14, v15 offset1:1
	v_add_u32_e32 v1, 0x14a8, v5
	ds_write2_b32 v1, v26, v27 offset1:1
	v_or_b32_e32 v1, s18, v19
	v_mad_i64_i32 v[14:15], s[20:21], v1, s74, v[2:3]
	global_load_dwordx4 v[24:27], v[14:15], off
	s_nop 0
	global_load_dword v14, v[6:7], off offset:192
	v_add_u32_e32 v1, 0x18c0, v5
	s_waitcnt vmcnt(0)
	v_pk_mul_f32 v[26:27], v[26:27], v[14:15] op_sel_hi:[1,0]
	v_pk_mul_f32 v[14:15], v[24:25], v[14:15] op_sel_hi:[1,0]
	ds_write2_b32 v1, v14, v15 offset1:1
	v_add_u32_e32 v1, 0x18c8, v5
	ds_write2_b32 v1, v26, v27 offset1:1
	v_or_b32_e32 v1, s18, v20
	v_mad_i64_i32 v[2:3], s[20:21], v1, s74, v[2:3]
	global_load_dwordx4 v[24:27], v[2:3], off
	s_nop 0
	global_load_dword v2, v[6:7], off offset:224
	v_add_u32_e32 v1, 0x1ce0, v5
	s_lshl_b64 s[18:19], s[18:19], 1
	s_waitcnt lgkmcnt(0)
	s_add_u32 s12, s12, s18
	s_addc_u32 s13, s13, s19
	s_add_i32 s10, s28, s5
	s_cmpk_gt_i32 s10, 0xaff
	s_waitcnt vmcnt(0)
	v_pk_mul_f32 v[6:7], v[26:27], v[2:3] op_sel_hi:[1,0]
	v_pk_mul_f32 v[2:3], v[24:25], v[2:3] op_sel_hi:[1,0]
	ds_write2_b32 v1, v2, v3 offset1:1
	v_add_u32_e32 v1, 0x1ce8, v5
	ds_write2_b32 v1, v6, v7 offset1:1
	s_waitcnt lgkmcnt(0)
	ds_read2_b32 v[6:7], v4 offset0:33 offset1:41
	ds_read2_b32 v[14:15], v4 offset1:8
	ds_read2_b32 v[28:29], v4 offset0:66 offset1:74
	ds_read2_b32 v[30:31], v4 offset0:99 offset1:107
	ds_read2_b32 v[32:33], v4 offset0:132 offset1:140
	ds_read2_b32 v[34:35], v4 offset0:165 offset1:173
	ds_read2_b32 v[36:37], v4 offset0:198 offset1:206
	ds_read2_b32 v[38:39], v4 offset0:231 offset1:239
	v_mov_b32_e32 v1, v113
	s_waitcnt lgkmcnt(6)
	v_cvt_pk_bf16_f32 v24, v14, v6
	v_add_u32_e32 v6, 0xfffff500, v9
	v_cndmask_b32_e32 v6, v9, v6, vcc
	v_lshlrev_b32_e32 v14, 1, v6
	v_and_b32_e32 v14, 0xffffff00, v14
	v_and_b32_e32 v6, 0x67, v6
	v_or3_b32 v40, v6, v23, v14
	v_lshl_add_u64 v[2:3], s[12:13], 0, v[0:1]
	s_mov_b64 s[12:13], 0x3000000
	v_ashrrev_i32_e32 v41, 31, v40
	v_lshl_add_u64 v[2:3], v[2:3], 0, s[12:13]
	v_lshlrev_b64 v[40:41], 11, v[40:41]
	s_waitcnt lgkmcnt(4)
	v_cvt_pk_bf16_f32 v25, v28, v30
	s_waitcnt lgkmcnt(2)
	v_cvt_pk_bf16_f32 v26, v32, v34
	s_waitcnt lgkmcnt(0)
	v_cvt_pk_bf16_f32 v27, v36, v38
	v_lshl_add_u64 v[40:41], v[2:3], 0, v[40:41]
	v_add_u32_e32 v6, 8, v9
	global_store_dwordx4 v[40:41], v[24:27], off
	v_cmp_lt_i32_e32 vcc, s85, v6
	s_nop 0
	v_cvt_pk_bf16_f32 v24, v15, v7
	v_add_u32_e32 v7, 0xfffff508, v9
	v_cndmask_b32_e32 v6, v6, v7, vcc
	v_lshlrev_b32_e32 v7, 1, v6
	v_and_b32_e32 v7, 0xffffff00, v7
	v_cndmask_b32_e32 v14, 0, v230, vcc
	v_and_b32_e32 v6, 0x6f, v6
	v_or3_b32 v6, v6, v14, v7
	v_ashrrev_i32_e32 v7, 31, v6
	v_lshlrev_b64 v[6:7], 11, v[6:7]
	v_cvt_pk_bf16_f32 v25, v29, v31
	v_cvt_pk_bf16_f32 v26, v33, v35
	v_cvt_pk_bf16_f32 v27, v37, v39
	v_lshl_add_u64 v[6:7], v[2:3], 0, v[6:7]
	global_store_dwordx4 v[6:7], v[24:27], off
	ds_read2_b32 v[6:7], v4 offset0:16 offset1:24
	ds_read2_b32 v[14:15], v4 offset0:49 offset1:57
	ds_read2_b32 v[28:29], v4 offset0:82 offset1:90
	ds_read2_b32 v[30:31], v4 offset0:115 offset1:123
	ds_read2_b32 v[32:33], v4 offset0:148 offset1:156
	ds_read2_b32 v[34:35], v4 offset0:181 offset1:189
	ds_read2_b32 v[36:37], v4 offset0:214 offset1:222
	ds_read2_b32 v[38:39], v4 offset0:247 offset1:255
	s_waitcnt lgkmcnt(6)
	v_cvt_pk_bf16_f32 v24, v6, v14
	v_add_u32_e32 v6, 16, v9
	v_cmp_lt_i32_e32 vcc, s85, v6
	v_add_u32_e32 v14, 0xfffff510, v9
	s_waitcnt lgkmcnt(4)
	v_cvt_pk_bf16_f32 v25, v28, v30
	v_cndmask_b32_e32 v6, v6, v14, vcc
	v_lshlrev_b32_e32 v14, 1, v6
	v_and_b32_e32 v14, 0xffffff00, v14
	v_cndmask_b32_e32 v23, 0, v230, vcc
	v_and_b32_e32 v6, 0x77, v6
	v_or3_b32 v40, v6, v23, v14
	v_add_u32_e32 v6, 24, v9
	v_cmp_lt_i32_e32 vcc, s85, v6
	v_add_u32_e32 v9, 0xfffff518, v9
	v_ashrrev_i32_e32 v41, 31, v40
	v_cndmask_b32_e32 v6, v6, v9, vcc
	v_lshlrev_b32_e32 v9, 1, v6
	v_lshlrev_b64 v[40:41], 11, v[40:41]
	v_and_b32_e32 v9, 0xffffff00, v9
	v_cndmask_b32_e32 v14, 0, v230, vcc
	v_and_b32_e32 v6, 0x7f, v6
	s_waitcnt lgkmcnt(2)
	v_cvt_pk_bf16_f32 v26, v32, v34
	s_waitcnt lgkmcnt(0)
	v_cvt_pk_bf16_f32 v27, v36, v38
	v_lshl_add_u64 v[40:41], v[2:3], 0, v[40:41]
	v_or3_b32 v6, v6, v14, v9
	global_store_dwordx4 v[40:41], v[24:27], off
	s_nop 1
	v_cvt_pk_bf16_f32 v24, v7, v15
	v_ashrrev_i32_e32 v7, 31, v6
	v_lshlrev_b64 v[6:7], 11, v[6:7]
	v_cvt_pk_bf16_f32 v25, v29, v31
	v_cvt_pk_bf16_f32 v26, v33, v35
	v_cvt_pk_bf16_f32 v27, v37, v39
	v_lshl_add_u64 v[2:3], v[2:3], 0, v[6:7]
	global_store_dwordx4 v[2:3], v[24:27], off
	s_waitcnt lgkmcnt(0)
	s_cbranch_scc1 .LBB0_655
	s_mov_b64 s[12:13], s[0:1]
	s_load_dwordx2 s[12:13], s[12:13], 0x20
	s_mul_hi_i32 s11, s10, 0x2e8ba2e9
	v_add_u32_e32 v9, 0x2520, v5
	s_waitcnt lgkmcnt(0)
	s_add_u32 s15, s12, s6
	s_addc_u32 s19, s13, s7
	s_mov_b64 s[12:13], s[0:1]
	s_load_dwordx2 s[12:13], s[12:13], 0x18
	s_waitcnt lgkmcnt(0)
	s_add_u32 s20, s12, s8
	s_addc_u32 s21, s13, s9
	s_lshr_b32 s18, s11, 31
	s_ashr_i32 s11, s11, 5
	s_add_i32 s11, s11, s18
	s_mul_i32 s18, s11, 0xb0
	s_sub_i32 s10, s10, s18
	s_lshl_b32 s10, s10, 5
	s_lshl_b32 s18, s11, 6
	s_ashr_i32 s11, s10, 31
	s_lshl_b64 s[22:23], s[10:11], 2
	s_add_u32 s22, s15, s22
	s_addc_u32 s23, s19, s23
	v_lshl_add_u64 v[2:3], s[22:23], 0, v[112:113]
	v_or_b32_e32 v6, s18, v8
	s_mov_b64 s[12:13], s[0:1]
	v_ashrrev_i32_e32 v7, 31, v6
	v_mad_i64_i32 v[14:15], s[22:23], v6, s74, v[2:3]
	global_load_dwordx4 v[24:27], v[14:15], off
	v_or_b32_e32 v47, s18, v11
	v_mad_i64_i32 v[48:49], vcc, v47, s74, v[2:3]
	global_load_dwordx4 v[74:77], v[48:49], off
	v_or_b32_e32 v47, s18, v13
	v_mad_i64_i32 v[48:49], vcc, v47, s74, v[2:3]
	global_load_dwordx4 v[78:81], v[48:49], off
	v_or_b32_e32 v47, s18, v16
	v_mad_i64_i32 v[48:49], vcc, v47, s74, v[2:3]
	global_load_dwordx4 v[82:85], v[48:49], off
	v_or_b32_e32 v47, s18, v17
	v_mad_i64_i32 v[48:49], vcc, v47, s74, v[2:3]
	global_load_dwordx4 v[86:89], v[48:49], off
	v_or_b32_e32 v47, s18, v18
	v_mad_i64_i32 v[48:49], vcc, v47, s74, v[2:3]
	global_load_dwordx4 v[90:93], v[48:49], off
	v_or_b32_e32 v47, s18, v19
	v_mad_i64_i32 v[48:49], vcc, v47, s74, v[2:3]
	global_load_dwordx4 v[94:97], v[48:49], off
	v_or_b32_e32 v47, s18, v20
	v_mad_i64_i32 v[48:49], vcc, v47, s74, v[2:3]
	global_load_dwordx4 v[98:101], v[48:49], off
	v_lshl_add_u64 v[14:15], v[6:7], 2, s[20:21]
	global_load_dword v14, v[14:15], off
	v_add_u32_e32 v7, 0x2100, v5
	s_ashr_i32 s19, s18, 31
	s_load_dwordx2 s[12:13], s[12:13], 0xe8
	s_waitcnt vmcnt(0)
	v_pk_mul_f32 v[26:27], v[26:27], v[14:15] op_sel_hi:[1,0]
	v_pk_mul_f32 v[14:15], v[24:25], v[14:15] op_sel_hi:[1,0]
	ds_write2_b32 v7, v14, v15 offset1:1
	v_add_u32_e32 v7, 0x2108, v5
	ds_write2_b32 v7, v26, v27 offset1:1
	v_or_b32_e32 v7, s18, v11
	v_mad_i64_i32 v[14:15], s[22:23], v7, s74, v[2:3]
	v_mov_b32_e32 v7, s19
	v_lshl_add_u64 v[6:7], v[6:7], 2, s[20:21]
	global_load_dwordx4 v[24:27], v[14:15], off
	s_nop 0
	global_load_dword v14, v[6:7], off offset:32
	s_waitcnt vmcnt(0)
	v_pk_mul_f32 v[26:27], v[26:27], v[14:15] op_sel_hi:[1,0]
	v_pk_mul_f32 v[14:15], v[24:25], v[14:15] op_sel_hi:[1,0]
	ds_write2_b32 v9, v14, v15 offset1:1
	v_add_u32_e32 v9, 0x2528, v5
	ds_write2_b32 v9, v26, v27 offset1:1
	v_or_b32_e32 v9, s18, v13
	v_mad_i64_i32 v[14:15], s[20:21], v9, s74, v[2:3]
	global_load_dwordx4 v[24:27], v[14:15], off
	s_nop 0
	global_load_dword v14, v[6:7], off offset:64
	v_add_u32_e32 v9, 0x2940, v5
	s_waitcnt vmcnt(0)
	v_pk_mul_f32 v[26:27], v[26:27], v[14:15] op_sel_hi:[1,0]
	v_pk_mul_f32 v[14:15], v[24:25], v[14:15] op_sel_hi:[1,0]
	ds_write2_b32 v9, v14, v15 offset1:1
	v_add_u32_e32 v9, 0x2948, v5
	ds_write2_b32 v9, v26, v27 offset1:1
	v_or_b32_e32 v9, s18, v16
	v_mad_i64_i32 v[14:15], s[20:21], v9, s74, v[2:3]
	global_load_dwordx4 v[24:27], v[14:15], off
	s_nop 0
	global_load_dword v14, v[6:7], off offset:96
	v_add_u32_e32 v9, 0x2d60, v5
	s_waitcnt vmcnt(0)
	v_pk_mul_f32 v[26:27], v[26:27], v[14:15] op_sel_hi:[1,0]
	v_pk_mul_f32 v[14:15], v[24:25], v[14:15] op_sel_hi:[1,0]
	ds_write2_b32 v9, v14, v15 offset1:1
	v_add_u32_e32 v9, 0x2d68, v5
	ds_write2_b32 v9, v26, v27 offset1:1
	v_or_b32_e32 v9, s18, v17
	v_mad_i64_i32 v[14:15], s[20:21], v9, s74, v[2:3]
	global_load_dwordx4 v[24:27], v[14:15], off
	s_nop 0
	global_load_dword v14, v[6:7], off offset:128
	v_add_u32_e32 v9, 0x3180, v5
	s_waitcnt vmcnt(0)
	v_pk_mul_f32 v[26:27], v[26:27], v[14:15] op_sel_hi:[1,0]
	v_pk_mul_f32 v[14:15], v[24:25], v[14:15] op_sel_hi:[1,0]
	ds_write2_b32 v9, v14, v15 offset1:1
	v_add_u32_e32 v9, 0x3188, v5
	ds_write2_b32 v9, v26, v27 offset1:1
	v_or_b32_e32 v9, s18, v18
	v_mad_i64_i32 v[14:15], s[20:21], v9, s74, v[2:3]
	global_load_dwordx4 v[24:27], v[14:15], off
	s_nop 0
	global_load_dword v14, v[6:7], off offset:160
	v_add_u32_e32 v9, 0x35a0, v5
	s_waitcnt vmcnt(0)
	v_pk_mul_f32 v[26:27], v[26:27], v[14:15] op_sel_hi:[1,0]
	v_pk_mul_f32 v[14:15], v[24:25], v[14:15] op_sel_hi:[1,0]
	ds_write2_b32 v9, v14, v15 offset1:1
	v_add_u32_e32 v9, 0x35a8, v5
	ds_write2_b32 v9, v26, v27 offset1:1
	v_or_b32_e32 v9, s18, v19
	v_mad_i64_i32 v[14:15], s[20:21], v9, s74, v[2:3]
	global_load_dwordx4 v[24:27], v[14:15], off
	s_nop 0
	global_load_dword v14, v[6:7], off offset:192
	v_add_u32_e32 v9, 0x39c0, v5
	s_waitcnt vmcnt(0)
	v_pk_mul_f32 v[26:27], v[26:27], v[14:15] op_sel_hi:[1,0]
	v_pk_mul_f32 v[14:15], v[24:25], v[14:15] op_sel_hi:[1,0]
	ds_write2_b32 v9, v14, v15 offset1:1
	v_add_u32_e32 v9, 0x39c8, v5
	ds_write2_b32 v9, v26, v27 offset1:1
	v_or_b32_e32 v9, s18, v20
	v_mad_i64_i32 v[2:3], s[20:21], v9, s74, v[2:3]
	global_load_dwordx4 v[24:27], v[2:3], off
	s_nop 0
	global_load_dword v2, v[6:7], off offset:224
	v_add_u32_e32 v9, 0x3de0, v5
	s_lshl_b64 s[18:19], s[18:19], 1
	s_waitcnt lgkmcnt(0)
	s_add_u32 s12, s12, s18
	s_addc_u32 s13, s13, s19
	s_waitcnt vmcnt(0)
	v_pk_mul_f32 v[6:7], v[26:27], v[2:3] op_sel_hi:[1,0]
	v_pk_mul_f32 v[2:3], v[24:25], v[2:3] op_sel_hi:[1,0]
	ds_write2_b32 v9, v2, v3 offset1:1
	v_add_u32_e32 v2, 0x3de8, v5
	ds_write2_b32 v2, v6, v7 offset1:1
	s_waitcnt lgkmcnt(0)
	v_lshl_add_u64 v[2:3], s[12:13], 0, v[0:1]
	v_add_u32_e32 v1, 0x2000, v4
	ds_read2_b32 v[6:7], v1 offset0:97 offset1:105
	ds_read2_b32 v[14:15], v1 offset0:64 offset1:72
	v_add_u32_e32 v9, 0x2400, v4
	ds_read2_b32 v[28:29], v1 offset0:130 offset1:138
	ds_read2_b32 v[30:31], v1 offset0:163 offset1:171
	ds_read2_b32 v[32:33], v1 offset0:196 offset1:204
	ds_read2_b32 v[34:35], v1 offset0:229 offset1:237
	ds_read2_b32 v[36:37], v9 offset0:6 offset1:14
	ds_read2_b32 v[38:39], v9 offset0:39 offset1:47
	s_waitcnt lgkmcnt(6)
	v_cvt_pk_bf16_f32 v24, v14, v6
	v_or_b32_e32 v6, s10, v8
	v_cmp_lt_i32_e32 vcc, s85, v6
	v_add_u32_e32 v14, 0xfffff500, v6
	s_mov_b64 s[12:13], 0x3000000
	v_cndmask_b32_e32 v6, v6, v14, vcc
	v_lshlrev_b32_e32 v14, 1, v6
	v_and_b32_e32 v14, 0xffffff00, v14
	v_cndmask_b32_e32 v23, 0, v230, vcc
	v_and_b32_e32 v6, 0x67, v6
	v_or3_b32 v40, v6, v23, v14
	v_ashrrev_i32_e32 v41, 31, v40
	v_lshl_add_u64 v[2:3], v[2:3], 0, s[12:13]
	v_lshlrev_b64 v[40:41], 11, v[40:41]
	s_waitcnt lgkmcnt(4)
	v_cvt_pk_bf16_f32 v25, v28, v30
	s_waitcnt lgkmcnt(2)
	v_cvt_pk_bf16_f32 v26, v32, v34
	s_waitcnt lgkmcnt(0)
	v_cvt_pk_bf16_f32 v27, v36, v38
	v_lshl_add_u64 v[40:41], v[2:3], 0, v[40:41]
	v_or_b32_e32 v6, s10, v11
	global_store_dwordx4 v[40:41], v[24:27], off
	v_cmp_lt_i32_e32 vcc, s85, v6
	s_nop 0
	v_cvt_pk_bf16_f32 v24, v15, v7
	v_add_u32_e32 v7, 0xfffff500, v6
	v_cndmask_b32_e32 v6, v6, v7, vcc
	v_lshlrev_b32_e32 v7, 1, v6
	v_and_b32_e32 v7, 0xffffff00, v7
	v_cndmask_b32_e32 v14, 0, v230, vcc
	v_and_b32_e32 v6, 0x6f, v6
	v_or3_b32 v6, v6, v14, v7
	v_ashrrev_i32_e32 v7, 31, v6
	v_lshlrev_b64 v[6:7], 11, v[6:7]
	v_cvt_pk_bf16_f32 v25, v29, v31
	v_cvt_pk_bf16_f32 v26, v33, v35
	v_cvt_pk_bf16_f32 v27, v37, v39
	v_lshl_add_u64 v[6:7], v[2:3], 0, v[6:7]
	global_store_dwordx4 v[6:7], v[24:27], off
	ds_read2_b32 v[6:7], v1 offset0:80 offset1:88
	ds_read2_b32 v[14:15], v1 offset0:113 offset1:121
	ds_read2_b32 v[28:29], v1 offset0:146 offset1:154
	ds_read2_b32 v[30:31], v1 offset0:179 offset1:187
	ds_read2_b32 v[32:33], v1 offset0:212 offset1:220
	ds_read2_b32 v[34:35], v1 offset0:245 offset1:253
	v_or_b32_e32 v1, s10, v13
	v_cmp_lt_i32_e32 vcc, s85, v1
	s_waitcnt lgkmcnt(4)
	v_cvt_pk_bf16_f32 v24, v6, v14
	v_add_u32_e32 v6, 0xfffff500, v1
	v_cndmask_b32_e32 v1, v1, v6, vcc
	v_lshlrev_b32_e32 v6, 1, v1
	ds_read2_b32 v[36:37], v9 offset0:22 offset1:30
	ds_read2_b32 v[38:39], v9 offset0:55 offset1:63
	v_and_b32_e32 v6, 0xffffff00, v6
	v_cndmask_b32_e32 v9, 0, v230, vcc
	v_and_b32_e32 v1, 0x77, v1
	v_or3_b32 v40, v1, v9, v6
	v_or_b32_e32 v1, s10, v16
	v_cmp_lt_i32_e32 vcc, s85, v1
	v_add_u32_e32 v6, 0xfffff500, v1
	v_ashrrev_i32_e32 v41, 31, v40
	v_cndmask_b32_e32 v1, v1, v6, vcc
	v_lshlrev_b32_e32 v6, 1, v1
	v_lshlrev_b64 v[40:41], 11, v[40:41]
	v_and_b32_e32 v6, 0xffffff00, v6
	v_cndmask_b32_e32 v9, 0, v230, vcc
	v_and_b32_e32 v1, 0x7f, v1
	s_waitcnt lgkmcnt(4)
	v_cvt_pk_bf16_f32 v25, v28, v30
	s_waitcnt lgkmcnt(2)
	v_cvt_pk_bf16_f32 v26, v32, v34
	s_waitcnt lgkmcnt(0)
	v_cvt_pk_bf16_f32 v27, v36, v38
	v_lshl_add_u64 v[40:41], v[2:3], 0, v[40:41]
	v_or3_b32 v6, v1, v9, v6
	global_store_dwordx4 v[40:41], v[24:27], off
	s_nop 1
	v_cvt_pk_bf16_f32 v24, v7, v15
	v_ashrrev_i32_e32 v7, 31, v6
	v_lshlrev_b64 v[6:7], 11, v[6:7]
	v_cvt_pk_bf16_f32 v25, v29, v31
	v_cvt_pk_bf16_f32 v26, v33, v35
	v_cvt_pk_bf16_f32 v27, v37, v39
	v_lshl_add_u64 v[2:3], v[2:3], 0, v[6:7]
	global_store_dwordx4 v[2:3], v[24:27], off
	s_waitcnt lgkmcnt(0)
	s_branch .LBB0_655

.LBB0_661:
	s_mov_b64 s[6:7], s[0:1]
	s_load_dwordx2 s[6:7], s[6:7], 0x28
	v_lshlrev_b32_e32 v112, 2, v10
	s_waitcnt vmcnt(0)
	v_add_u32_e32 v5, 0x420, v4
	s_waitcnt lgkmcnt(0)
	s_add_u32 s9, s6, s4
	s_addc_u32 s11, s7, s5
	s_ashr_i32 s8, s12, 31
	s_lshr_b32 s8, s8, 27
	s_add_i32 s8, s12, s8
	s_ashr_i32 s10, s8, 5
	s_lshl_b32 s14, s10, 10
	s_sub_i32 s14, s13, s14
	s_ashr_i32 s15, s14, 31
	s_lshl_b32 s8, s10, 6
	s_lshl_b64 s[14:15], s[14:15], 2
	s_add_u32 s14, s9, s14
	v_or_b32_e32 v6, s8, v8
	s_addc_u32 s15, s11, s15
	v_ashrrev_i32_e32 v7, 31, v6
	v_lshl_add_u64 v[0:1], s[14:15], 0, v[112:113]
	v_lshlrev_b64 v[6:7], 12, v[6:7]
	s_mov_b64 s[6:7], s[0:1]
	v_lshl_add_u64 v[6:7], v[0:1], 0, v[6:7]
	global_load_dwordx4 v[22:25], v[6:7], off
	v_or_b32_e32 v46, s8, v11
	v_ashrrev_i32_e32 v47, 31, v46
	v_lshlrev_b64 v[48:49], 12, v[46:47]
	v_lshl_add_u64 v[50:51], v[0:1], 0, v[48:49]
	global_load_dwordx4 v[74:77], v[50:51], off
	v_or_b32_e32 v46, s8, v13
	v_ashrrev_i32_e32 v47, 31, v46
	v_lshlrev_b64 v[48:49], 12, v[46:47]
	v_lshl_add_u64 v[50:51], v[0:1], 0, v[48:49]
	global_load_dwordx4 v[78:81], v[50:51], off
	v_or_b32_e32 v46, s8, v16
	v_ashrrev_i32_e32 v47, 31, v46
	v_lshlrev_b64 v[48:49], 12, v[46:47]
	v_lshl_add_u64 v[50:51], v[0:1], 0, v[48:49]
	global_load_dwordx4 v[82:85], v[50:51], off
	v_or_b32_e32 v46, s8, v17
	v_ashrrev_i32_e32 v47, 31, v46
	v_lshlrev_b64 v[48:49], 12, v[46:47]
	v_lshl_add_u64 v[50:51], v[0:1], 0, v[48:49]
	global_load_dwordx4 v[86:89], v[50:51], off
	v_or_b32_e32 v46, s8, v18
	v_ashrrev_i32_e32 v47, 31, v46
	v_lshlrev_b64 v[48:49], 12, v[46:47]
	v_lshl_add_u64 v[50:51], v[0:1], 0, v[48:49]
	global_load_dwordx4 v[90:93], v[50:51], off
	v_or_b32_e32 v46, s8, v19
	v_ashrrev_i32_e32 v47, 31, v46
	v_lshlrev_b64 v[48:49], 12, v[46:47]
	v_lshl_add_u64 v[50:51], v[0:1], 0, v[48:49]
	global_load_dwordx4 v[94:97], v[50:51], off
	v_or_b32_e32 v46, s8, v20
	v_ashrrev_i32_e32 v47, 31, v46
	v_lshlrev_b64 v[48:49], 12, v[46:47]
	v_lshl_add_u64 v[50:51], v[0:1], 0, v[48:49]
	global_load_dwordx4 v[98:101], v[50:51], off
	v_or_b32_e32 v6, s8, v11
	v_ashrrev_i32_e32 v7, 31, v6
	v_lshlrev_b64 v[6:7], 12, v[6:7]
	s_load_dwordx2 s[6:7], s[6:7], 0xe8
	v_lshl_add_u64 v[6:7], v[0:1], 0, v[6:7]
	s_ashr_i32 s9, s8, 31
	s_mul_i32 s10, s10, 0xffd40000
	v_add_u32_e32 v40, s10, v3
	v_ashrrev_i32_e32 v41, 31, v40
	s_waitcnt vmcnt(0)
	ds_write2_b32 v4, v22, v23 offset1:1
	ds_write2_b32 v4, v24, v25 offset0:2 offset1:3
	global_load_dwordx4 v[22:25], v[6:7], off
	v_or_b32_e32 v6, s8, v13
	v_ashrrev_i32_e32 v7, 31, v6
	v_lshlrev_b64 v[6:7], 12, v[6:7]
	v_lshl_add_u64 v[6:7], v[0:1], 0, v[6:7]
	s_waitcnt vmcnt(0)
	ds_write2_b32 v5, v22, v23 offset1:1
	v_add_u32_e32 v5, 0x428, v4
	ds_write2_b32 v5, v24, v25 offset1:1
	global_load_dwordx4 v[22:25], v[6:7], off
	v_or_b32_e32 v6, s8, v16
	v_ashrrev_i32_e32 v7, 31, v6
	v_add_u32_e32 v5, 0x840, v4
	v_lshlrev_b64 v[6:7], 12, v[6:7]
	v_lshl_add_u64 v[6:7], v[0:1], 0, v[6:7]
	s_waitcnt vmcnt(0)
	ds_write2_b32 v5, v22, v23 offset1:1
	v_add_u32_e32 v5, 0x848, v4
	ds_write2_b32 v5, v24, v25 offset1:1
	global_load_dwordx4 v[22:25], v[6:7], off
	v_or_b32_e32 v6, s8, v17
	v_ashrrev_i32_e32 v7, 31, v6
	v_add_u32_e32 v5, 0xc60, v4
	v_lshlrev_b64 v[6:7], 12, v[6:7]
	v_lshl_add_u64 v[6:7], v[0:1], 0, v[6:7]
	s_waitcnt vmcnt(0)
	ds_write2_b32 v5, v22, v23 offset1:1
	v_add_u32_e32 v5, 0xc68, v4
	ds_write2_b32 v5, v24, v25 offset1:1
	global_load_dwordx4 v[22:25], v[6:7], off
	v_or_b32_e32 v6, s8, v18
	v_ashrrev_i32_e32 v7, 31, v6
	v_add_u32_e32 v5, 0x1080, v4
	v_lshlrev_b64 v[6:7], 12, v[6:7]
	v_lshl_add_u64 v[6:7], v[0:1], 0, v[6:7]
	s_waitcnt vmcnt(0)
	ds_write2_b32 v5, v22, v23 offset1:1
	v_add_u32_e32 v5, 0x1088, v4
	ds_write2_b32 v5, v24, v25 offset1:1
	global_load_dwordx4 v[22:25], v[6:7], off
	v_or_b32_e32 v6, s8, v19
	v_ashrrev_i32_e32 v7, 31, v6
	v_add_u32_e32 v5, 0x14a0, v4
	v_lshlrev_b64 v[6:7], 12, v[6:7]
	v_lshl_add_u64 v[6:7], v[0:1], 0, v[6:7]
	s_waitcnt vmcnt(0)
	ds_write2_b32 v5, v22, v23 offset1:1
	v_add_u32_e32 v5, 0x14a8, v4
	ds_write2_b32 v5, v24, v25 offset1:1
	global_load_dwordx4 v[22:25], v[6:7], off
	v_or_b32_e32 v6, s8, v20
	v_ashrrev_i32_e32 v7, 31, v6
	v_add_u32_e32 v5, 0x18c0, v4
	v_lshlrev_b64 v[6:7], 12, v[6:7]
	v_lshl_add_u64 v[0:1], v[0:1], 0, v[6:7]
	s_lshl_b64 s[8:9], s[8:9], 1
	s_waitcnt lgkmcnt(0)
	s_add_u32 s6, s6, s8
	s_addc_u32 s7, s7, s9
	s_waitcnt vmcnt(0)
	ds_write2_b32 v5, v22, v23 offset1:1
	v_add_u32_e32 v5, 0x18c8, v4
	ds_write2_b32 v5, v24, v25 offset1:1
	global_load_dwordx4 v[22:25], v[0:1], off
	v_add_u32_e32 v0, 0x1ce0, v4
	v_mov_b32_e32 v1, v113
	s_waitcnt vmcnt(0)
	ds_write2_b32 v0, v22, v23 offset1:1
	v_add_u32_e32 v0, 0x1ce8, v4
	ds_write2_b32 v0, v24, v25 offset1:1
	s_waitcnt lgkmcnt(0)
	ds_read2_b32 v[14:15], v2 offset0:33 offset1:41
	ds_read2_b32 v[26:27], v2 offset1:8
	ds_read2_b32 v[28:29], v2 offset0:66 offset1:74
	ds_read2_b32 v[30:31], v2 offset0:99 offset1:107
	ds_read2_b32 v[32:33], v2 offset0:132 offset1:140
	ds_read2_b32 v[34:35], v2 offset0:165 offset1:173
	ds_read2_b32 v[36:37], v2 offset0:198 offset1:206
	ds_read2_b32 v[38:39], v2 offset0:231 offset1:239
	v_lshlrev_b32_e32 v0, 1, v12
	v_lshl_add_u64 v[6:7], s[6:7], 0, v[0:1]
	v_lshl_add_u64 v[6:7], v[6:7], 0, s[20:21]
	s_waitcnt lgkmcnt(6)
	v_cvt_pk_bf16_f32 v22, v26, v14
	s_waitcnt lgkmcnt(4)
	v_cvt_pk_bf16_f32 v23, v28, v30
	s_waitcnt lgkmcnt(2)
	v_cvt_pk_bf16_f32 v24, v32, v34
	s_waitcnt lgkmcnt(0)
	v_cvt_pk_bf16_f32 v25, v36, v38
	v_lshl_add_u64 v[42:43], v[40:41], 1, v[6:7]
	v_add_u32_e32 v14, 0x5800, v40
	global_store_dwordx4 v[42:43], v[22:25], off
	v_add_u32_e32 v42, 0xb000, v40
	v_ashrrev_i32_e32 v43, 31, v42
	v_cvt_pk_bf16_f32 v22, v27, v15
	v_ashrrev_i32_e32 v15, 31, v14
	v_cvt_pk_bf16_f32 v23, v29, v31
	v_cvt_pk_bf16_f32 v24, v33, v35
	v_cvt_pk_bf16_f32 v25, v37, v39
	v_lshl_add_u64 v[14:15], v[14:15], 1, v[6:7]
	global_store_dwordx4 v[14:15], v[22:25], off
	ds_read2_b32 v[14:15], v2 offset0:49 offset1:57
	ds_read2_b32 v[26:27], v2 offset0:16 offset1:24
	ds_read2_b32 v[28:29], v2 offset0:82 offset1:90
	ds_read2_b32 v[30:31], v2 offset0:115 offset1:123
	ds_read2_b32 v[32:33], v2 offset0:148 offset1:156
	ds_read2_b32 v[34:35], v2 offset0:181 offset1:189
	ds_read2_b32 v[36:37], v2 offset0:214 offset1:222
	ds_read2_b32 v[38:39], v2 offset0:247 offset1:255
	v_lshl_add_u64 v[42:43], v[42:43], 1, v[6:7]
	s_waitcnt lgkmcnt(6)
	v_cvt_pk_bf16_f32 v22, v26, v14
	s_waitcnt lgkmcnt(4)
	v_cvt_pk_bf16_f32 v23, v28, v30
	s_waitcnt lgkmcnt(2)
	v_cvt_pk_bf16_f32 v24, v32, v34
	s_waitcnt lgkmcnt(0)
	v_cvt_pk_bf16_f32 v25, v36, v38
	v_add_u32_e32 v14, 0x10800, v40
	global_store_dwordx4 v[42:43], v[22:25], off
	s_add_i32 s6, s28, s12
	s_cmpk_gt_i32 s6, 0x57f
	v_cvt_pk_bf16_f32 v22, v27, v15
	v_ashrrev_i32_e32 v15, 31, v14
	v_cvt_pk_bf16_f32 v23, v29, v31
	v_cvt_pk_bf16_f32 v24, v33, v35
	v_cvt_pk_bf16_f32 v25, v37, v39
	v_lshl_add_u64 v[6:7], v[14:15], 1, v[6:7]
	global_store_dwordx4 v[6:7], v[22:25], off
	s_waitcnt lgkmcnt(0)
	s_cbranch_scc1 .LBB0_660
	s_mov_b64 s[8:9], s[0:1]
	s_load_dwordx2 s[8:9], s[8:9], 0x28
	v_add_u32_e32 v5, 0x2100, v4
	v_add_u32_e32 v9, 0x2400, v2
	s_movk_i32 s3, 0xb00
	s_waitcnt lgkmcnt(0)
	s_add_u32 s11, s8, s4
	s_addc_u32 s18, s9, s5
	s_ashr_i32 s7, s6, 31
	s_lshr_b32 s7, s7, 27
	s_add_i32 s7, s6, s7
	s_and_b32 s10, s7, 0x7ffffe0
	s_sub_i32 s6, s6, s10
	s_lshl_b32 s7, s7, 1
	s_lshl_b32 s6, s6, 5
	s_and_b32 s10, s7, 0xffffffc0
	s_ashr_i32 s7, s6, 31
	s_lshl_b64 s[14:15], s[6:7], 2
	s_add_u32 s14, s11, s14
	v_or_b32_e32 v14, s10, v8
	s_addc_u32 s15, s18, s15
	v_ashrrev_i32_e32 v15, 31, v14
	v_lshl_add_u64 v[6:7], s[14:15], 0, v[112:113]
	v_lshlrev_b64 v[14:15], 12, v[14:15]
	s_mov_b64 s[8:9], s[0:1]
	v_lshl_add_u64 v[14:15], v[6:7], 0, v[14:15]
	global_load_dwordx4 v[22:25], v[14:15], off
	v_or_b32_e32 v46, s10, v11
	v_ashrrev_i32_e32 v47, 31, v46
	v_lshlrev_b64 v[48:49], 12, v[46:47]
	v_lshl_add_u64 v[50:51], v[6:7], 0, v[48:49]
	global_load_dwordx4 v[74:77], v[50:51], off
	v_or_b32_e32 v46, s10, v13
	v_ashrrev_i32_e32 v47, 31, v46
	v_lshlrev_b64 v[48:49], 12, v[46:47]
	v_lshl_add_u64 v[50:51], v[6:7], 0, v[48:49]
	global_load_dwordx4 v[78:81], v[50:51], off
	v_or_b32_e32 v46, s10, v16
	v_ashrrev_i32_e32 v47, 31, v46
	v_lshlrev_b64 v[48:49], 12, v[46:47]
	v_lshl_add_u64 v[50:51], v[6:7], 0, v[48:49]
	global_load_dwordx4 v[82:85], v[50:51], off
	v_or_b32_e32 v46, s10, v17
	v_ashrrev_i32_e32 v47, 31, v46
	v_lshlrev_b64 v[48:49], 12, v[46:47]
	v_lshl_add_u64 v[50:51], v[6:7], 0, v[48:49]
	global_load_dwordx4 v[86:89], v[50:51], off
	v_or_b32_e32 v46, s10, v18
	v_ashrrev_i32_e32 v47, 31, v46
	v_lshlrev_b64 v[48:49], 12, v[46:47]
	v_lshl_add_u64 v[50:51], v[6:7], 0, v[48:49]
	global_load_dwordx4 v[90:93], v[50:51], off
	v_or_b32_e32 v46, s10, v19
	v_ashrrev_i32_e32 v47, 31, v46
	v_lshlrev_b64 v[48:49], 12, v[46:47]
	v_lshl_add_u64 v[50:51], v[6:7], 0, v[48:49]
	global_load_dwordx4 v[94:97], v[50:51], off
	v_or_b32_e32 v46, s10, v20
	v_ashrrev_i32_e32 v47, 31, v46
	v_lshlrev_b64 v[48:49], 12, v[46:47]
	v_lshl_add_u64 v[50:51], v[6:7], 0, v[48:49]
	global_load_dwordx4 v[98:101], v[50:51], off
	v_or_b32_e32 v14, s10, v11
	v_ashrrev_i32_e32 v15, 31, v14
	v_lshlrev_b64 v[14:15], 12, v[14:15]
	v_lshl_add_u64 v[14:15], v[6:7], 0, v[14:15]
	s_load_dwordx2 s[8:9], s[8:9], 0xe8
	s_ashr_i32 s11, s10, 31
	s_waitcnt vmcnt(0)
	ds_write2_b32 v5, v22, v23 offset1:1
	v_add_u32_e32 v5, 0x2108, v4
	ds_write2_b32 v5, v24, v25 offset1:1
	global_load_dwordx4 v[22:25], v[14:15], off
	v_or_b32_e32 v14, s10, v13
	v_ashrrev_i32_e32 v15, 31, v14
	v_add_u32_e32 v5, 0x2520, v4
	v_lshlrev_b64 v[14:15], 12, v[14:15]
	v_lshl_add_u64 v[14:15], v[6:7], 0, v[14:15]
	s_waitcnt vmcnt(0)
	ds_write2_b32 v5, v22, v23 offset1:1
	v_add_u32_e32 v5, 0x2528, v4
	ds_write2_b32 v5, v24, v25 offset1:1
	global_load_dwordx4 v[22:25], v[14:15], off
	v_or_b32_e32 v14, s10, v16
	v_ashrrev_i32_e32 v15, 31, v14
	v_add_u32_e32 v5, 0x2940, v4
	v_lshlrev_b64 v[14:15], 12, v[14:15]
	v_lshl_add_u64 v[14:15], v[6:7], 0, v[14:15]
	s_waitcnt vmcnt(0)
	ds_write2_b32 v5, v22, v23 offset1:1
	v_add_u32_e32 v5, 0x2948, v4
	ds_write2_b32 v5, v24, v25 offset1:1
	global_load_dwordx4 v[22:25], v[14:15], off
	v_or_b32_e32 v14, s10, v17
	v_ashrrev_i32_e32 v15, 31, v14
	v_add_u32_e32 v5, 0x2d60, v4
	v_lshlrev_b64 v[14:15], 12, v[14:15]
	v_lshl_add_u64 v[14:15], v[6:7], 0, v[14:15]
	s_waitcnt vmcnt(0)
	ds_write2_b32 v5, v22, v23 offset1:1
	v_add_u32_e32 v5, 0x2d68, v4
	ds_write2_b32 v5, v24, v25 offset1:1
	global_load_dwordx4 v[22:25], v[14:15], off
	v_or_b32_e32 v14, s10, v18
	v_ashrrev_i32_e32 v15, 31, v14
	v_add_u32_e32 v5, 0x3180, v4
	v_lshlrev_b64 v[14:15], 12, v[14:15]
	v_lshl_add_u64 v[14:15], v[6:7], 0, v[14:15]
	s_waitcnt vmcnt(0)
	ds_write2_b32 v5, v22, v23 offset1:1
	v_add_u32_e32 v5, 0x3188, v4
	ds_write2_b32 v5, v24, v25 offset1:1
	global_load_dwordx4 v[22:25], v[14:15], off
	v_or_b32_e32 v14, s10, v19
	v_ashrrev_i32_e32 v15, 31, v14
	v_add_u32_e32 v5, 0x35a0, v4
	v_lshlrev_b64 v[14:15], 12, v[14:15]
	v_lshl_add_u64 v[14:15], v[6:7], 0, v[14:15]
	s_waitcnt vmcnt(0)
	ds_write2_b32 v5, v22, v23 offset1:1
	v_add_u32_e32 v5, 0x35a8, v4
	ds_write2_b32 v5, v24, v25 offset1:1
	global_load_dwordx4 v[22:25], v[14:15], off
	v_or_b32_e32 v14, s10, v20
	v_ashrrev_i32_e32 v15, 31, v14
	v_add_u32_e32 v5, 0x39c0, v4
	v_lshlrev_b64 v[14:15], 12, v[14:15]
	v_lshl_add_u64 v[6:7], v[6:7], 0, v[14:15]
	s_lshl_b64 s[10:11], s[10:11], 1
	s_waitcnt lgkmcnt(0)
	s_add_u32 s8, s8, s10
	s_addc_u32 s9, s9, s11
	v_lshl_add_u64 v[0:1], s[8:9], 0, v[0:1]
	v_lshl_add_u64 v[0:1], v[0:1], 0, s[20:21]
	s_waitcnt vmcnt(0)
	ds_write2_b32 v5, v22, v23 offset1:1
	v_add_u32_e32 v5, 0x39c8, v4
	ds_write2_b32 v5, v24, v25 offset1:1
	global_load_dwordx4 v[22:25], v[6:7], off
	v_add_u32_e32 v5, 0x3de0, v4
	s_waitcnt vmcnt(0)
	ds_write2_b32 v5, v22, v23 offset1:1
	v_add_u32_e32 v5, 0x3de8, v4
	ds_write2_b32 v5, v24, v25 offset1:1
	s_waitcnt lgkmcnt(0)
	v_add_u32_e32 v5, 0x2000, v2
	ds_read2_b32 v[6:7], v5 offset0:97 offset1:105
	ds_read2_b32 v[14:15], v5 offset0:64 offset1:72
	ds_read2_b32 v[26:27], v5 offset0:130 offset1:138
	ds_read2_b32 v[28:29], v5 offset0:163 offset1:171
	ds_read2_b32 v[30:31], v5 offset0:196 offset1:204
	ds_read2_b32 v[32:33], v5 offset0:229 offset1:237
	ds_read2_b32 v[34:35], v9 offset0:6 offset1:14
	ds_read2_b32 v[36:37], v9 offset0:39 offset1:47
	s_waitcnt lgkmcnt(6)
	v_cvt_pk_bf16_f32 v22, v14, v6
	v_or_b32_e32 v6, s6, v8
	v_mul_lo_u32 v38, v6, s3
	v_ashrrev_i32_e32 v39, 31, v38
	v_or_b32_e32 v6, s6, v11
	s_waitcnt lgkmcnt(4)
	v_cvt_pk_bf16_f32 v23, v26, v28
	s_waitcnt lgkmcnt(2)
	v_cvt_pk_bf16_f32 v24, v30, v32
	s_waitcnt lgkmcnt(0)
	v_cvt_pk_bf16_f32 v25, v34, v36
	v_lshl_add_u64 v[38:39], v[38:39], 1, v[0:1]
	v_mul_lo_u32 v6, v6, s3
	global_store_dwordx4 v[38:39], v[22:25], off
	s_nop 1
	v_cvt_pk_bf16_f32 v22, v15, v7
	v_ashrrev_i32_e32 v7, 31, v6
	v_cvt_pk_bf16_f32 v23, v27, v29
	v_cvt_pk_bf16_f32 v24, v31, v33
	v_cvt_pk_bf16_f32 v25, v35, v37
	v_lshl_add_u64 v[6:7], v[6:7], 1, v[0:1]
	global_store_dwordx4 v[6:7], v[22:25], off
	ds_read2_b32 v[6:7], v5 offset0:113 offset1:121
	ds_read2_b32 v[14:15], v5 offset0:80 offset1:88
	ds_read2_b32 v[26:27], v5 offset0:146 offset1:154
	ds_read2_b32 v[28:29], v5 offset0:179 offset1:187
	ds_read2_b32 v[30:31], v5 offset0:212 offset1:220
	ds_read2_b32 v[32:33], v5 offset0:245 offset1:253
	ds_read2_b32 v[34:35], v9 offset0:22 offset1:30
	ds_read2_b32 v[36:37], v9 offset0:55 offset1:63
	v_or_b32_e32 v5, s6, v13
	v_mul_lo_u32 v38, v5, s3
	v_ashrrev_i32_e32 v39, 31, v38
	v_or_b32_e32 v5, s6, v16
	s_waitcnt lgkmcnt(6)
	v_cvt_pk_bf16_f32 v22, v14, v6
	s_waitcnt lgkmcnt(4)
	v_cvt_pk_bf16_f32 v23, v26, v28
	s_waitcnt lgkmcnt(2)
	v_cvt_pk_bf16_f32 v24, v30, v32
	s_waitcnt lgkmcnt(0)
	v_cvt_pk_bf16_f32 v25, v34, v36
	v_lshl_add_u64 v[38:39], v[38:39], 1, v[0:1]
	v_mul_lo_u32 v6, v5, s3
	global_store_dwordx4 v[38:39], v[22:25], off
	s_nop 1
	v_cvt_pk_bf16_f32 v22, v15, v7
	v_ashrrev_i32_e32 v7, 31, v6
	v_cvt_pk_bf16_f32 v23, v27, v29
	v_cvt_pk_bf16_f32 v24, v31, v33
	v_cvt_pk_bf16_f32 v25, v35, v37
	v_lshl_add_u64 v[0:1], v[6:7], 1, v[0:1]
	global_store_dwordx4 v[0:1], v[22:25], off
	s_waitcnt lgkmcnt(0)
	s_branch .LBB0_660

.LBB0_1002:
.LBB0_1003:
	v_readlane_b32 s4, v255, 15
	v_readlane_b32 s5, v255, 16
	s_andn2_b64 vcc, exec, s[4:5]
	s_cbranch_vccnz .LBB0_1059
	s_add_u32 s44, s34, s39
	s_addc_u32 s45, s35, s38
	s_waitcnt lgkmcnt(0)
	s_add_u32 s39, s42, s39
	s_addc_u32 s38, s43, s38
	v_readlane_b32 s50, v255, 14
	s_waitcnt vmcnt(0)
	v_and_b32_e32 v0, 15, v224
	v_and_b32_e32 v1, 7, v224
	v_lshlrev_b32_e32 v0, 4, v0
	v_lshlrev_b32_e32 v1, 4, v1
	s_mov_b32 s12, s39
	s_mov_b32 s13, s38
	global_load_dwordx4 v[2:5], v0, s[44:45]
	global_load_dwordx4 v[6:9], v1, s[44:45] offset:256
	global_load_dwordx4 v[10:13], v0, s[12:13]
	global_load_dwordx4 v[14:17], v1, s[12:13] offset:256
	s_waitcnt vmcnt(2)
	v_max3_f32 v18, |v2|, |v3|, |v4|
	v_max3_f32 v19, |v6|, |v7|, |v8|
	v_max3_f32 v18, v18, |v5|, |v9|
	s_waitcnt vmcnt(0)
	v_max3_f32 v20, |v10|, |v11|, |v12|
	v_max3_f32 v21, |v14|, |v15|, |v16|
	v_max3_f32 v20, v20, |v13|, |v17|
	v_max_f32_e32 v18, v18, v19
	v_max_f32_e32 v20, v20, v21
	s_nop 0
	v_max_f32_dpp v18, v18, v18 row_ror:8 row_mask:0xf bank_mask:0xf
	v_max_f32_dpp v20, v20, v20 row_ror:8 row_mask:0xf bank_mask:0xf
	s_nop 0
	v_max_f32_dpp v18, v18, v18 row_ror:4 row_mask:0xf bank_mask:0xf
	v_max_f32_dpp v20, v20, v20 row_ror:4 row_mask:0xf bank_mask:0xf
	s_nop 0
	v_max_f32_dpp v18, v18, v18 row_ror:2 row_mask:0xf bank_mask:0xf
	v_max_f32_dpp v20, v20, v20 row_ror:2 row_mask:0xf bank_mask:0xf
	s_nop 0
	v_max_f32_dpp v1, v18, v18 row_ror:1 row_mask:0xf bank_mask:0xf
	v_max_f32_dpp v0, v20, v20 row_ror:1 row_mask:0xf bank_mask:0xf
	v_mul_f32_e32 v0, v1, v0
	s_nop 0
	v_readfirstlane_b32 s100, v0
	s_branch .LBB0_1007

.LBB0_1007:
	s_mov_b64 s[4:5], s[0:1]
	s_load_dwordx2 s[8:9], s[4:5], 0xe8
	s_mov_b64 s[4:5], s[0:1]
	s_load_dwordx2 s[30:31], s[4:5], 0x10
	s_mov_b64 s[4:5], s[0:1]
	s_load_dwordx2 s[6:7], s[4:5], 0xe8
	s_mov_b64 s[4:5], s[0:1]
	s_mov_b64 s[10:11], s[0:1]
	s_load_dwordx2 s[4:5], s[4:5], 0xe8
	s_load_dwordx2 s[34:35], s[10:11], 0xe8
	s_mov_b64 s[10:11], 0
	s_waitcnt vmcnt(2)
	s_ashr_i32 s3, s50, 3
	s_and_b32 s3, s3, -8
	v_readlane_b32 s10, v255, 12
	s_or_b32 s10, s3, s10
	s_mul_hi_i32 s3, s10, 0x2aaaaaab
	s_lshr_b32 s11, s3, 31
	s_ashr_i32 s3, s3, 1
	s_add_i32 s3, s3, s11
	s_mul_i32 s11, s3, 12
	s_sub_i32 s51, s10, s11
	s_mul_i32 s12, s51, 0x60
	s_ashr_i32 s13, s12, 31
	s_lshl_b64 s[12:13], s[12:13], 1
	s_waitcnt lgkmcnt(0)
	s_add_u32 s8, s8, s12
	s_addc_u32 s9, s9, s13
	s_add_u32 s40, s8, 0x14200000
	s_addc_u32 s41, s9, 0
	s_lshl_b32 s8, s50, 8
	s_and_b32 s12, s8, 0x3f00
	s_ashr_i32 s11, s10, 31
	s_lshl_b32 s3, s3, 14
	s_mul_i32 s14, s10, 0x300000
	s_lshl_b64 s[8:9], s[10:11], 21
	s_or_b32 s47, s3, s12
	s_mul_hi_i32 s13, s10, 0x300000
	s_add_u32 s3, s6, s14
	s_addc_u32 s6, s7, s13
	s_add_u32 s42, s3, 0x18a00000
	s_addc_u32 s43, s6, 0
	s_add_u32 s3, s4, s8
	v_mov_b32_e32 v0, s100
	s_addc_u32 s4, s5, s9
	v_mul_f32_e32 v0, 0x42c00000, v0
	s_add_u32 s62, s3, 0x5200000
	v_mul_f32_e32 v0, 0x3e16c740, v0
	s_mov_b32 s3, 0x3f83d70a
	v_fma_f32 v176, v0, s3, 0.5
	s_mov_b32 s3, 0x42400000
	v_cmp_ngt_f32_e32 vcc, s3, v176
	s_addc_u32 s63, s4, 0
	s_mov_b64 s[4:5], -1
	s_and_b64 vcc, exec, vcc
	s_cbranch_vccz .LBB0_1034
	v_mov_b32_e32 v0, v224
	v_mov_b32_e32 v100, v113
	v_ashrrev_i32_e32 v1, 31, v0
	v_lshl_add_u64 v[2:3], v[0:1], 4, s[42:43]
	global_load_dwordx4 v[12:15], v[2:3], off
	v_mov_b32_e32 v101, v113
	v_add_u32_e32 v70, 0x200, v0
	v_mov_b32_e32 v102, v113
	v_mov_b32_e32 v103, v113
	v_mov_b64_e32 v[96:97], v[100:101]
	v_cmp_lt_i32_e64 s[6:7], s2, v0
	v_cmp_gt_i32_e64 s[4:5], s89, v0
	v_ashrrev_i32_e32 v71, 31, v70
	v_mov_b64_e32 v[98:99], v[102:103]
	s_and_saveexec_b64 s[8:9], s[4:5]
	s_cbranch_execz .LBB0_1012
	v_lshl_add_u64 v[2:3], v[70:71], 4, s[42:43]
	global_load_dwordx4 v[96:99], v[2:3], off

.LBB0_1253:
	v_readlane_b32 s6, v255, 22
	v_readlane_b32 s7, v255, 23
	s_andn2_b64 vcc, exec, s[6:7]
	s_cbranch_vccnz .LBB0_1314
	v_readlane_b32 s6, v255, 38
	s_lshl_b32 s90, s6, 6
	s_lshl_b32 s24, s6, 3
	s_lshl_b32 s25, s4, 1
	s_lshl_b64 s[10:11], s[90:91], 2
	s_mov_b32 s30, s75
	v_readlane_b32 s7, v255, 39
	s_load_dwordx2 s[12:13], s[0:1], 0x48
	s_load_dwordx2 s[16:17], s[0:1], 0x50
	v_readlane_b32 s20, v255, 28
	v_readlane_b32 s21, v255, 29
	s_waitcnt lgkmcnt(0)
	s_add_u32 s18, s12, s20
	s_addc_u32 s19, s13, s21
	s_add_u32 s20, s16, s20
	s_addc_u32 s21, s17, s21
	s_waitcnt vmcnt(0)
	v_and_b32_e32 v0, 15, v224
	v_lshlrev_b32_e32 v0, 4, v0
	global_load_dwordx4 v[2:5], v0, s[18:19]
	global_load_dwordx4 v[6:9], v0, s[20:21]
	s_waitcnt vmcnt(1)
	v_max3_f32 v10, |v2|, |v3|, |v4|
	s_waitcnt vmcnt(0)
	v_max3_f32 v12, |v6|, |v7|, |v8|
	v_max_f32_e64 v10, v10, |v5|
	v_max_f32_e64 v12, v12, |v9|
	s_nop 0
	v_max_f32_dpp v10, v10, v10 row_ror:8 row_mask:0xf bank_mask:0xf
	v_max_f32_dpp v12, v12, v12 row_ror:8 row_mask:0xf bank_mask:0xf
	s_nop 0
	v_max_f32_dpp v10, v10, v10 row_ror:4 row_mask:0xf bank_mask:0xf
	v_max_f32_dpp v12, v12, v12 row_ror:4 row_mask:0xf bank_mask:0xf
	s_nop 0
	v_max_f32_dpp v10, v10, v10 row_ror:2 row_mask:0xf bank_mask:0xf
	v_max_f32_dpp v12, v12, v12 row_ror:2 row_mask:0xf bank_mask:0xf
	s_nop 0
	v_max_f32_dpp v1, v10, v10 row_ror:1 row_mask:0xf bank_mask:0xf
	v_max_f32_dpp v0, v12, v12 row_ror:1 row_mask:0xf bank_mask:0xf
	v_mul_f32_e32 v0, v1, v0
	s_nop 0
	v_readfirstlane_b32 s100, v0
	s_branch .LBB0_1257

.LBB0_1257:
	s_mov_b64 s[4:5], s[0:1]
	s_load_dwordx2 s[14:15], s[4:5], 0xe8
	s_mov_b64 s[4:5], s[0:1]
	s_load_dwordx2 s[6:7], s[4:5], 0x48
	s_mov_b64 s[4:5], s[0:1]
	s_load_dwordx2 s[16:17], s[4:5], 0x50
	s_mov_b64 s[4:5], s[0:1]
	s_mov_b64 s[4:5], s[0:1]
	s_load_dwordx2 s[8:9], s[4:5], 0xe8
	s_mov_b64 s[4:5], s[0:1]
	s_mov_b64 s[12:13], s[0:1]
	s_load_dwordx2 s[4:5], s[4:5], 0xe8
	s_load_dwordx2 s[12:13], s[12:13], 0xe8
	v_readlane_b32 s20, v255, 28
	v_readlane_b32 s21, v255, 29
	s_waitcnt lgkmcnt(0)
	s_add_u32 s18, s6, s20
	s_addc_u32 s19, s7, s21
	s_add_u32 s20, s16, s20
	s_addc_u32 s21, s17, s21
	s_mov_b64 s[16:17], 0
	s_waitcnt vmcnt(2)
	s_ashr_i32 s3, s30, 8
	s_lshl_b32 s16, s3, 2
	s_bfe_u32 s31, s30, 0x20006
	s_add_i32 s16, s16, s24
	s_or_b32 s20, s16, s31
	s_ashr_i32 s21, s20, 31
	s_add_u32 s14, s14, s25
	s_addc_u32 s15, s15, 0
	s_lshl_b32 s16, s31, 7
	s_add_u32 s14, s14, s16
	s_addc_u32 s15, s15, 0
	s_add_u32 s18, s14, 0x9200000
	s_addc_u32 s19, s15, 0
	s_lshl_b32 s14, s30, 8
	s_and_b32 s14, s14, 0x3f00
	s_add_u32 s16, s6, s10
	s_addc_u32 s17, s7, s11
	s_lshl_b32 s3, s3, 14
	s_lshl_b64 s[6:7], s[20:21], 15
	s_or_b32 s34, s3, s14
	s_add_u32 s3, s8, s6
	s_addc_u32 s8, s9, s7
	s_add_u32 s14, s3, 0x1000000
	s_addc_u32 s15, s8, 0
	s_add_u32 s3, s4, s6
	v_mov_b32_e32 v0, s100
	s_addc_u32 s4, s5, s7
	v_mul_f32_e32 v0, 0x42800000, v0
	s_add_u32 s20, s3, 0x1100000
	v_mul_f32_e32 v0, 0x3e38aa3b, v0
	s_mov_b32 s3, 0x3f83d70a
	v_fma_f32 v159, v0, s3, 0.5
	s_mov_b32 s3, 0x42400000
	v_cmp_ngt_f32_e32 vcc, s3, v159
	s_addc_u32 s21, s4, 0
	s_mov_b64 s[4:5], -1
	s_and_b64 vcc, exec, vcc
	s_cbranch_vccz .LBB0_1285
	v_mov_b32_e32 v0, v224
	s_nop 0
	v_ashrrev_i32_e32 v1, 31, v0
	v_lshl_add_u64 v[2:3], v[0:1], 4, s[14:15]
	global_load_dwordx4 v[12:15], v[2:3], off
	v_lshlrev_b64 v[56:57], 3, v[0:1]
	v_cmp_gt_i32_e64 s[4:5], 0, v0
	v_cmp_lt_i32_e64 s[6:7], -1, v0
	v_lshl_add_u64 v[54:55], v[56:57], 1, s[14:15]
	s_and_saveexec_b64 s[8:9], s[6:7]
	s_xor_b64 s[8:9], exec, s[8:9]
	s_cbranch_execz .LBB0_1262
	v_add_co_u32_e32 v2, vcc, 0x2000, v54
	s_nop 1
	v_addc_co_u32_e32 v3, vcc, 0, v55, vcc
	global_load_dwordx4 v[8:11], v[2:3], off
